# rolling counted lgkmcnt waits at every other P.V site (attn0 diagonal loop and tails, all attn1 loops)
# speedup vs baseline: 1.0036x; 1.0036x over previous
.LBB0_328:
	v_add_f32_e32 v2, 0, v230
	v_add_f32_e32 v2, v232, v2
	v_add_f32_e32 v2, v228, v2
	v_add_f32_e32 v2, v231, v2
	v_add_f32_e32 v2, v226, v2
	v_add_f32_e32 v2, v229, v2
	v_add_f32_e32 v2, v225, v2
	v_add_f32_e32 v2, v227, v2
	v_add_f32_e32 v2, v222, v2
	v_add_f32_e32 v2, v224, v2
	v_add_f32_e32 v2, v220, v2
	v_add_f32_e32 v2, v223, v2
	v_exp_f32_e32 v10, v128
	v_add_f32_e32 v2, v218, v2
	v_exp_f32_e32 v11, v129
	v_add_f32_e32 v2, v221, v2
	v_exp_f32_e32 v12, v130
	v_add_f32_e32 v2, v217, v2
	v_exp_f32_e32 v13, v131
	v_add_f32_e32 v2, v219, v2
	v_exp_f32_e32 v15, v132
	v_add_f32_e32 v2, v10, v2
	v_exp_f32_e32 v17, v133
	v_add_f32_e32 v2, v11, v2
	v_exp_f32_e32 v18, v134
	v_add_f32_e32 v2, v12, v2
	v_exp_f32_e32 v19, v135
	v_add_f32_e32 v2, v13, v2
	v_exp_f32_e32 v20, v136
	v_add_f32_e32 v2, v15, v2
	v_exp_f32_e32 v21, v137
	v_add_f32_e32 v2, v17, v2
	v_exp_f32_e32 v22, v138
	v_add_f32_e32 v2, v18, v2
	v_exp_f32_e32 v23, v139
	v_add_f32_e32 v2, v19, v2
	v_exp_f32_e32 v24, v140
	v_add_f32_e32 v2, v20, v2
	v_exp_f32_e32 v25, v141
	v_add_f32_e32 v2, v21, v2
	v_exp_f32_e32 v26, v142
	v_add_f32_e32 v2, v22, v2
	v_exp_f32_e32 v27, v143
	v_add_f32_e32 v2, v23, v2
	v_add_f32_e32 v2, v24, v2
	v_add_f32_e32 v2, v25, v2
	v_add_f32_e32 v2, v26, v2
	v_add_f32_e32 v215, v27, v2
	v_mov_b32_e32 v216, v215
	v_cvt_pk_bf16_f32 v2, v230, v232
	v_cvt_pk_bf16_f32 v3, v228, v231
	v_cvt_pk_bf16_f32 v4, v226, v229
	v_cvt_pk_bf16_f32 v5, v225, v227
	v_cvt_pk_bf16_f32 v6, v222, v224
	v_cvt_pk_bf16_f32 v7, v220, v223
	v_cvt_pk_bf16_f32 v8, v218, v221
	v_cvt_pk_bf16_f32 v9, v217, v219
	v_cvt_pk_bf16_f32 v10, v10, v11
	v_cvt_pk_bf16_f32 v11, v12, v13
	v_cvt_pk_bf16_f32 v12, v15, v17
	v_cvt_pk_bf16_f32 v13, v18, v19
	v_cvt_pk_bf16_f32 v18, v20, v21
	v_cvt_pk_bf16_f32 v19, v22, v23
	v_cvt_pk_bf16_f32 v20, v24, v25
	v_cvt_pk_bf16_f32 v21, v26, v27
	s_nop 1
	v_permlane32_swap_b32_e32 v215, v216
	s_cmp_gt_i32 s57, s6
	s_cbranch_scc1 .LBB0_330
	v_add_u32_e32 v15, s87, v206
	ds_read_b64_tr_b16 v[22:23], v15 offset:0
	ds_read_b64_tr_b16 v[24:25], v15 offset:0x800
	ds_read_b64_tr_b16 v[26:27], v15 offset:0x1000
	ds_read_b64_tr_b16 v[28:29], v15 offset:0x1800
	ds_read_b64_tr_b16 v[128:129], v15 offset:0x2000
	ds_read_b64_tr_b16 v[130:131], v15 offset:0x2800
	ds_read_b64_tr_b16 v[132:133], v15 offset:0x3000
	ds_read_b64_tr_b16 v[134:135], v15 offset:0x3800
	s_waitcnt lgkmcnt(6)
	s_nop 0
	v_mfma_f32_32x32x16_bf16 v[32:47], v[2:5], v[22:25], v[32:47]
	ds_read_b64_tr_b16 v[22:23], v15 offset:0x200
	ds_read_b64_tr_b16 v[24:25], v15 offset:0xa00
	s_waitcnt lgkmcnt(6)
	v_mfma_f32_32x32x16_bf16 v[32:47], v[6:9], v[26:29], v[32:47]
	ds_read_b64_tr_b16 v[26:27], v15 offset:0x1200
	ds_read_b64_tr_b16 v[28:29], v15 offset:0x1a00
	s_waitcnt lgkmcnt(6)
	v_mfma_f32_32x32x16_bf16 v[32:47], v[10:13], v[128:131], v[32:47]
	ds_read_b64_tr_b16 v[128:129], v15 offset:0x2200
	ds_read_b64_tr_b16 v[130:131], v15 offset:0x2a00
	s_waitcnt lgkmcnt(6)
	v_mfma_f32_32x32x16_bf16 v[32:47], v[18:21], v[132:135], v[32:47]
	ds_read_b64_tr_b16 v[132:133], v15 offset:0x3200
	ds_read_b64_tr_b16 v[134:135], v15 offset:0x3a00
	s_waitcnt lgkmcnt(6)
	v_mfma_f32_32x32x16_bf16 v[48:63], v[2:5], v[22:25], v[48:63]
	ds_read_b64_tr_b16 v[22:23], v15 offset:0x400
	ds_read_b64_tr_b16 v[24:25], v15 offset:0xc00
	s_waitcnt lgkmcnt(6)
	v_mfma_f32_32x32x16_bf16 v[48:63], v[6:9], v[26:29], v[48:63]
	ds_read_b64_tr_b16 v[26:27], v15 offset:0x1400
	ds_read_b64_tr_b16 v[28:29], v15 offset:0x1c00
	s_waitcnt lgkmcnt(6)
	v_mfma_f32_32x32x16_bf16 v[48:63], v[10:13], v[128:131], v[48:63]
	ds_read_b64_tr_b16 v[128:129], v15 offset:0x2400
	ds_read_b64_tr_b16 v[130:131], v15 offset:0x2c00
	s_waitcnt lgkmcnt(6)
	v_mfma_f32_32x32x16_bf16 v[48:63], v[18:21], v[132:135], v[48:63]
	ds_read_b64_tr_b16 v[132:133], v15 offset:0x3400
	ds_read_b64_tr_b16 v[134:135], v15 offset:0x3c00
	s_waitcnt lgkmcnt(6)
	v_mfma_f32_32x32x16_bf16 v[64:79], v[2:5], v[22:25], v[64:79]
	ds_read_b64_tr_b16 v[22:23], v15 offset:0x600
	ds_read_b64_tr_b16 v[24:25], v15 offset:0xe00
	s_waitcnt lgkmcnt(6)
	v_mfma_f32_32x32x16_bf16 v[64:79], v[6:9], v[26:29], v[64:79]
	ds_read_b64_tr_b16 v[26:27], v15 offset:0x1600
	ds_read_b64_tr_b16 v[28:29], v15 offset:0x1e00
	s_waitcnt lgkmcnt(6)
	v_mfma_f32_32x32x16_bf16 v[64:79], v[10:13], v[128:131], v[64:79]
	ds_read_b64_tr_b16 v[128:129], v15 offset:0x2600
	ds_read_b64_tr_b16 v[130:131], v15 offset:0x2e00
	s_waitcnt lgkmcnt(6)
	v_mfma_f32_32x32x16_bf16 v[64:79], v[18:21], v[132:135], v[64:79]
	ds_read_b64_tr_b16 v[132:133], v15 offset:0x3600
	ds_read_b64_tr_b16 v[134:135], v15 offset:0x3e00
	s_waitcnt lgkmcnt(6)
	v_mfma_f32_32x32x16_bf16 v[80:95], v[2:5], v[22:25], v[80:95]
	s_waitcnt lgkmcnt(4)
	v_mfma_f32_32x32x16_bf16 v[80:95], v[6:9], v[26:29], v[80:95]
	s_waitcnt lgkmcnt(2)
	v_mfma_f32_32x32x16_bf16 v[80:95], v[10:13], v[128:131], v[80:95]
	s_waitcnt lgkmcnt(0)
	v_mfma_f32_32x32x16_bf16 v[80:95], v[18:21], v[132:135], v[80:95]

.LBB0_347:
	v_cndmask_b32_e64 v23, v2, v214, s[4:5]
	v_mul_f32_e32 v2, 0xbe0293ee, v23
	v_fmamk_f32 v3, v112, 0x3e0293ee, v2
	v_fmamk_f32 v4, v113, 0x3e0293ee, v2
	v_exp_f32_e32 v3, v3
	v_fmamk_f32 v5, v114, 0x3e0293ee, v2
	v_exp_f32_e32 v4, v4
	v_fmamk_f32 v6, v115, 0x3e0293ee, v2
	v_exp_f32_e32 v5, v5
	v_fmamk_f32 v7, v116, 0x3e0293ee, v2
	v_fmamk_f32 v8, v117, 0x3e0293ee, v2
	v_fmamk_f32 v9, v118, 0x3e0293ee, v2
	v_fmamk_f32 v10, v119, 0x3e0293ee, v2
	v_fmamk_f32 v11, v120, 0x3e0293ee, v2
	v_fmamk_f32 v12, v121, 0x3e0293ee, v2
	v_fmamk_f32 v13, v122, 0x3e0293ee, v2
	v_fmamk_f32 v15, v123, 0x3e0293ee, v2
	v_fmamk_f32 v17, v124, 0x3e0293ee, v2
	v_fmamk_f32 v18, v125, 0x3e0293ee, v2
	v_fmamk_f32 v19, v126, 0x3e0293ee, v2
	v_fmamk_f32 v20, v127, 0x3e0293ee, v2
	v_fmamk_f32 v21, v96, 0x3e0293ee, v2
	v_fmamk_f32 v22, v97, 0x3e0293ee, v2
	v_fmamk_f32 v24, v98, 0x3e0293ee, v2
	v_fmamk_f32 v25, v99, 0x3e0293ee, v2
	v_fmamk_f32 v26, v100, 0x3e0293ee, v2
	v_fmamk_f32 v27, v101, 0x3e0293ee, v2
	v_fmamk_f32 v28, v102, 0x3e0293ee, v2
	v_fmamk_f32 v29, v103, 0x3e0293ee, v2
	v_fmamk_f32 v30, v104, 0x3e0293ee, v2
	v_fmamk_f32 v31, v105, 0x3e0293ee, v2
	v_fmamk_f32 v96, v106, 0x3e0293ee, v2
	v_fmamk_f32 v97, v107, 0x3e0293ee, v2
	v_fmamk_f32 v98, v108, 0x3e0293ee, v2
	v_fmamk_f32 v99, v109, 0x3e0293ee, v2
	v_fmamk_f32 v100, v110, 0x3e0293ee, v2
	v_fmac_f32_e32 v2, 0x3e0293ee, v111
	v_exp_f32_e32 v6, v6
	v_exp_f32_e32 v7, v7
	v_exp_f32_e32 v103, v2
	v_add_f32_e32 v2, 0, v3
	v_exp_f32_e32 v8, v8
	v_add_f32_e32 v2, v4, v2
	v_exp_f32_e32 v9, v9
	v_add_f32_e32 v2, v5, v2
	v_exp_f32_e32 v10, v10
	v_add_f32_e32 v2, v6, v2
	v_exp_f32_e32 v11, v11
	v_add_f32_e32 v2, v7, v2
	v_exp_f32_e32 v12, v12
	v_add_f32_e32 v2, v8, v2
	v_exp_f32_e32 v13, v13
	v_add_f32_e32 v2, v9, v2
	v_exp_f32_e32 v15, v15
	v_add_f32_e32 v2, v10, v2
	v_exp_f32_e32 v101, v17
	v_add_f32_e32 v2, v11, v2
	v_exp_f32_e32 v18, v18
	v_add_f32_e32 v2, v12, v2
	v_exp_f32_e32 v19, v19
	v_add_f32_e32 v2, v13, v2
	v_exp_f32_e32 v20, v20
	v_add_f32_e32 v2, v15, v2
	v_exp_f32_e32 v21, v21
	v_add_f32_e32 v2, v101, v2
	v_exp_f32_e32 v102, v22
	v_add_f32_e32 v2, v18, v2
	v_exp_f32_e32 v24, v24
	v_add_f32_e32 v2, v19, v2
	v_exp_f32_e32 v25, v25
	v_add_f32_e32 v2, v20, v2
	v_exp_f32_e32 v26, v26
	v_add_f32_e32 v2, v21, v2
	v_exp_f32_e32 v27, v27
	v_add_f32_e32 v2, v102, v2
	v_exp_f32_e32 v28, v28
	v_add_f32_e32 v2, v24, v2
	v_exp_f32_e32 v29, v29
	v_add_f32_e32 v2, v25, v2
	v_exp_f32_e32 v30, v30
	v_add_f32_e32 v2, v26, v2
	v_exp_f32_e32 v31, v31
	v_add_f32_e32 v2, v27, v2
	v_exp_f32_e32 v96, v96
	v_add_f32_e32 v2, v28, v2
	v_exp_f32_e32 v97, v97
	v_add_f32_e32 v2, v29, v2
	v_exp_f32_e32 v98, v98
	v_add_f32_e32 v2, v30, v2
	v_exp_f32_e32 v99, v99
	v_add_f32_e32 v2, v31, v2
	v_exp_f32_e32 v100, v100
	v_add_f32_e32 v2, v96, v2
	v_add_f32_e32 v2, v97, v2
	v_add_f32_e32 v2, v98, v2
	v_add_f32_e32 v2, v99, v2
	v_add_f32_e32 v2, v100, v2
	v_add_f32_e32 v17, v103, v2
	v_mov_b32_e32 v22, v17
	v_cvt_pk_bf16_f32 v2, v3, v4
	v_cvt_pk_bf16_f32 v3, v5, v6
	v_cvt_pk_bf16_f32 v4, v7, v8
	v_cvt_pk_bf16_f32 v5, v9, v10
	v_cvt_pk_bf16_f32 v6, v11, v12
	v_cvt_pk_bf16_f32 v7, v13, v15
	v_cvt_pk_bf16_f32 v8, v101, v18
	v_cvt_pk_bf16_f32 v9, v19, v20
	v_cvt_pk_bf16_f32 v10, v21, v102
	v_cvt_pk_bf16_f32 v11, v24, v25
	v_cvt_pk_bf16_f32 v12, v26, v27
	v_cvt_pk_bf16_f32 v13, v28, v29
	v_cvt_pk_bf16_f32 v18, v30, v31
	v_cvt_pk_bf16_f32 v19, v96, v97
	v_cvt_pk_bf16_f32 v20, v98, v99
	v_cvt_pk_bf16_f32 v21, v100, v103
	s_nop 1
	v_permlane32_swap_b32_e32 v17, v22
	s_andn2_b64 vcc, exec, s[70:71]
	s_cbranch_vccnz .LBB0_349
	v_add_u32_e32 v15, s83, v206
	ds_read_b64_tr_b16 v[24:25], v15 offset:0
	ds_read_b64_tr_b16 v[26:27], v15 offset:0x800
	ds_read_b64_tr_b16 v[28:29], v15 offset:0x1000
	ds_read_b64_tr_b16 v[30:31], v15 offset:0x1800
	ds_read_b64_tr_b16 v[96:97], v15 offset:0x2000
	ds_read_b64_tr_b16 v[98:99], v15 offset:0x2800
	ds_read_b64_tr_b16 v[100:101], v15 offset:0x3000
	ds_read_b64_tr_b16 v[102:103], v15 offset:0x3800
	s_waitcnt lgkmcnt(6)
	s_nop 0
	v_mfma_f32_32x32x16_bf16 v[32:47], v[2:5], v[24:27], v[32:47]
	ds_read_b64_tr_b16 v[24:25], v15 offset:0x200
	ds_read_b64_tr_b16 v[26:27], v15 offset:0xa00
	s_waitcnt lgkmcnt(6)
	v_mfma_f32_32x32x16_bf16 v[32:47], v[6:9], v[28:31], v[32:47]
	ds_read_b64_tr_b16 v[28:29], v15 offset:0x1200
	ds_read_b64_tr_b16 v[30:31], v15 offset:0x1a00
	s_waitcnt lgkmcnt(6)
	v_mfma_f32_32x32x16_bf16 v[32:47], v[10:13], v[96:99], v[32:47]
	ds_read_b64_tr_b16 v[96:97], v15 offset:0x2200
	ds_read_b64_tr_b16 v[98:99], v15 offset:0x2a00
	s_waitcnt lgkmcnt(6)
	v_mfma_f32_32x32x16_bf16 v[32:47], v[18:21], v[100:103], v[32:47]
	ds_read_b64_tr_b16 v[100:101], v15 offset:0x3200
	ds_read_b64_tr_b16 v[102:103], v15 offset:0x3a00
	s_waitcnt lgkmcnt(6)
	v_mfma_f32_32x32x16_bf16 v[48:63], v[2:5], v[24:27], v[48:63]
	ds_read_b64_tr_b16 v[24:25], v15 offset:0x400
	ds_read_b64_tr_b16 v[26:27], v15 offset:0xc00
	s_waitcnt lgkmcnt(6)
	v_mfma_f32_32x32x16_bf16 v[48:63], v[6:9], v[28:31], v[48:63]
	ds_read_b64_tr_b16 v[28:29], v15 offset:0x1400
	ds_read_b64_tr_b16 v[30:31], v15 offset:0x1c00
	s_waitcnt lgkmcnt(6)
	v_mfma_f32_32x32x16_bf16 v[48:63], v[10:13], v[96:99], v[48:63]
	ds_read_b64_tr_b16 v[96:97], v15 offset:0x2400
	ds_read_b64_tr_b16 v[98:99], v15 offset:0x2c00
	s_waitcnt lgkmcnt(6)
	v_mfma_f32_32x32x16_bf16 v[48:63], v[18:21], v[100:103], v[48:63]
	ds_read_b64_tr_b16 v[100:101], v15 offset:0x3400
	ds_read_b64_tr_b16 v[102:103], v15 offset:0x3c00
	s_waitcnt lgkmcnt(6)
	v_mfma_f32_32x32x16_bf16 v[64:79], v[2:5], v[24:27], v[64:79]
	ds_read_b64_tr_b16 v[24:25], v15 offset:0x600
	ds_read_b64_tr_b16 v[26:27], v15 offset:0xe00
	s_waitcnt lgkmcnt(6)
	v_mfma_f32_32x32x16_bf16 v[64:79], v[6:9], v[28:31], v[64:79]
	ds_read_b64_tr_b16 v[28:29], v15 offset:0x1600
	ds_read_b64_tr_b16 v[30:31], v15 offset:0x1e00
	s_waitcnt lgkmcnt(6)
	v_mfma_f32_32x32x16_bf16 v[64:79], v[10:13], v[96:99], v[64:79]
	ds_read_b64_tr_b16 v[96:97], v15 offset:0x2600
	ds_read_b64_tr_b16 v[98:99], v15 offset:0x2e00
	s_waitcnt lgkmcnt(6)
	v_mfma_f32_32x32x16_bf16 v[64:79], v[18:21], v[100:103], v[64:79]
	ds_read_b64_tr_b16 v[100:101], v15 offset:0x3600
	ds_read_b64_tr_b16 v[102:103], v15 offset:0x3e00
	s_waitcnt lgkmcnt(6)
	v_mfma_f32_32x32x16_bf16 v[80:95], v[2:5], v[24:27], v[80:95]
	s_waitcnt lgkmcnt(4)
	v_mfma_f32_32x32x16_bf16 v[80:95], v[6:9], v[28:31], v[80:95]
	s_waitcnt lgkmcnt(2)
	v_mfma_f32_32x32x16_bf16 v[80:95], v[10:13], v[96:99], v[80:95]
	s_waitcnt lgkmcnt(0)
	v_mfma_f32_32x32x16_bf16 v[80:95], v[18:21], v[100:103], v[80:95]

.LBB0_362:
	v_exp_f32_e32 v233, v128
	v_exp_f32_e32 v236, v129
	v_exp_f32_e32 v237, v130
	v_exp_f32_e32 v240, v131
	v_exp_f32_e32 v241, v132
	v_exp_f32_e32 v243, v133
	v_exp_f32_e32 v244, v134
	v_exp_f32_e32 v245, v135
	v_exp_f32_e32 v213, v136
	v_exp_f32_e32 v215, v137
	v_exp_f32_e32 v216, v138
	v_exp_f32_e32 v234, v139
	v_exp_f32_e32 v235, v140
	v_exp_f32_e32 v238, v141
	v_exp_f32_e32 v239, v142
	v_exp_f32_e32 v242, v143
	v_add_f32_e32 v1, 0, v230
	v_cndmask_b32_e64 v2, 0, 1, s[10:11]
	s_mov_b64 s[4:5], -1
	s_cmp_ge_i32 s56, s44
	v_add_f32_e32 v1, v232, v1
	v_cmp_ne_u32_e64 s[2:3], 1, v2
	s_cbranch_scc0 .LBB0_366
	v_add_f32_e32 v2, v228, v1
	v_add_f32_e32 v2, v231, v2
	v_add_f32_e32 v2, v226, v2
	v_add_f32_e32 v2, v229, v2
	v_add_f32_e32 v2, v225, v2
	v_add_f32_e32 v2, v227, v2
	v_add_f32_e32 v2, v222, v2
	v_add_f32_e32 v2, v224, v2
	v_add_f32_e32 v2, v220, v2
	v_add_f32_e32 v2, v223, v2
	v_add_f32_e32 v2, v218, v2
	v_add_f32_e32 v2, v221, v2
	v_add_f32_e32 v2, v217, v2
	v_add_f32_e32 v2, v219, v2
	v_add_f32_e32 v2, v233, v2
	v_add_f32_e32 v2, v236, v2
	v_add_f32_e32 v2, v237, v2
	v_add_f32_e32 v2, v240, v2
	v_add_f32_e32 v2, v241, v2
	v_add_f32_e32 v2, v243, v2
	v_add_f32_e32 v2, v244, v2
	v_add_f32_e32 v2, v245, v2
	v_add_f32_e32 v2, v213, v2
	v_add_f32_e32 v2, v215, v2
	v_add_f32_e32 v2, v216, v2
	v_add_f32_e32 v2, v234, v2
	v_add_f32_e32 v2, v235, v2
	v_add_f32_e32 v2, v238, v2
	v_add_f32_e32 v2, v239, v2
	v_add_f32_e32 v14, v242, v2
	v_mov_b32_e32 v17, v14
	v_cvt_pk_bf16_f32 v2, v230, v232
	v_cvt_pk_bf16_f32 v3, v228, v231
	v_cvt_pk_bf16_f32 v4, v226, v229
	v_cvt_pk_bf16_f32 v5, v225, v227
	v_cvt_pk_bf16_f32 v6, v222, v224
	v_cvt_pk_bf16_f32 v7, v220, v223
	v_cvt_pk_bf16_f32 v8, v218, v221
	v_cvt_pk_bf16_f32 v9, v217, v219
	v_cvt_pk_bf16_f32 v10, v233, v236
	v_cvt_pk_bf16_f32 v11, v237, v240
	v_cvt_pk_bf16_f32 v12, v241, v243
	v_cvt_pk_bf16_f32 v13, v244, v245
	v_cvt_pk_bf16_f32 v18, v213, v215
	v_cvt_pk_bf16_f32 v19, v216, v234
	v_cvt_pk_bf16_f32 v20, v235, v238
	v_cvt_pk_bf16_f32 v21, v239, v242
	s_nop 1
	v_permlane32_swap_b32_e32 v14, v17
	v_mov_b64_e32 v[158:159], v[94:95]
	v_mov_b64_e32 v[142:143], v[78:79]
	v_mov_b64_e32 v[126:127], v[62:63]
	v_mov_b64_e32 v[110:111], v[46:47]
	s_and_b64 vcc, exec, s[2:3]
	v_mov_b64_e32 v[156:157], v[92:93]
	v_mov_b64_e32 v[154:155], v[90:91]
	v_mov_b64_e32 v[152:153], v[88:89]
	v_mov_b64_e32 v[150:151], v[86:87]
	v_mov_b64_e32 v[148:149], v[84:85]
	v_mov_b64_e32 v[146:147], v[82:83]
	v_mov_b64_e32 v[144:145], v[80:81]
	v_mov_b64_e32 v[140:141], v[76:77]
	v_mov_b64_e32 v[138:139], v[74:75]
	v_mov_b64_e32 v[136:137], v[72:73]
	v_mov_b64_e32 v[134:135], v[70:71]
	v_mov_b64_e32 v[132:133], v[68:69]
	v_mov_b64_e32 v[130:131], v[66:67]
	v_mov_b64_e32 v[128:129], v[64:65]
	v_mov_b64_e32 v[124:125], v[60:61]
	v_mov_b64_e32 v[122:123], v[58:59]
	v_mov_b64_e32 v[120:121], v[56:57]
	v_mov_b64_e32 v[118:119], v[54:55]
	v_mov_b64_e32 v[116:117], v[52:53]
	v_mov_b64_e32 v[114:115], v[50:51]
	v_mov_b64_e32 v[112:113], v[48:49]
	v_mov_b64_e32 v[108:109], v[44:45]
	v_mov_b64_e32 v[106:107], v[42:43]
	v_mov_b64_e32 v[104:105], v[40:41]
	v_mov_b64_e32 v[102:103], v[38:39]
	v_mov_b64_e32 v[100:101], v[36:37]
	v_mov_b64_e32 v[98:99], v[34:35]
	v_mov_b64_e32 v[96:97], v[32:33]
	s_cbranch_vccnz .LBB0_365
	v_add_u32_e32 v30, s74, v206
	ds_read_b64_tr_b16 v[22:23], v30 offset:0
	ds_read_b64_tr_b16 v[24:25], v30 offset:0x800
	ds_read_b64_tr_b16 v[26:27], v30 offset:0x1000
	ds_read_b64_tr_b16 v[28:29], v30 offset:0x1800
	ds_read_b64_tr_b16 v[112:113], v30 offset:0x2000
	ds_read_b64_tr_b16 v[114:115], v30 offset:0x2800
	ds_read_b64_tr_b16 v[116:117], v30 offset:0x3000
	ds_read_b64_tr_b16 v[118:119], v30 offset:0x3800
	s_waitcnt lgkmcnt(6)
	s_nop 0
	v_mfma_f32_32x32x16_bf16 v[96:111], v[2:5], v[22:25], v[32:47]
	ds_read_b64_tr_b16 v[22:23], v30 offset:0x200
	ds_read_b64_tr_b16 v[24:25], v30 offset:0xa00
	s_waitcnt lgkmcnt(6)
	v_mfma_f32_32x32x16_bf16 v[96:111], v[6:9], v[26:29], v[96:111]
	ds_read_b64_tr_b16 v[26:27], v30 offset:0x1200
	ds_read_b64_tr_b16 v[28:29], v30 offset:0x1a00
	ds_read_b64_tr_b16 v[128:129], v30 offset:0x2200
	ds_read_b64_tr_b16 v[130:131], v30 offset:0x2a00
	ds_read_b64_tr_b16 v[132:133], v30 offset:0x3200
	ds_read_b64_tr_b16 v[134:135], v30 offset:0x3a00
	s_waitcnt lgkmcnt(6)
	v_mfma_f32_32x32x16_bf16 v[96:111], v[10:13], v[112:115], v[96:111]
	s_waitcnt lgkmcnt(6)
	v_mfma_f32_32x32x16_bf16 v[96:111], v[18:21], v[116:119], v[96:111]
	s_waitcnt lgkmcnt(6)
	v_mfma_f32_32x32x16_bf16 v[112:127], v[2:5], v[22:25], v[48:63]
	ds_read_b64_tr_b16 v[22:23], v30 offset:0x400
	ds_read_b64_tr_b16 v[24:25], v30 offset:0xc00
	s_waitcnt lgkmcnt(6)
	v_mfma_f32_32x32x16_bf16 v[112:127], v[6:9], v[26:29], v[112:127]
	ds_read_b64_tr_b16 v[26:27], v30 offset:0x1400
	ds_read_b64_tr_b16 v[28:29], v30 offset:0x1c00
	ds_read_b64_tr_b16 v[144:145], v30 offset:0x2400
	ds_read_b64_tr_b16 v[146:147], v30 offset:0x2c00
	ds_read_b64_tr_b16 v[148:149], v30 offset:0x3400
	ds_read_b64_tr_b16 v[150:151], v30 offset:0x3c00
	s_waitcnt lgkmcnt(6)
	v_mfma_f32_32x32x16_bf16 v[112:127], v[10:13], v[128:131], v[112:127]
	s_waitcnt lgkmcnt(6)
	v_mfma_f32_32x32x16_bf16 v[112:127], v[18:21], v[132:135], v[112:127]
	s_waitcnt lgkmcnt(6)
	v_mfma_f32_32x32x16_bf16 v[128:143], v[2:5], v[22:25], v[64:79]
	ds_read_b64_tr_b16 v[22:23], v30 offset:0x600
	ds_read_b64_tr_b16 v[24:25], v30 offset:0xe00
	s_waitcnt lgkmcnt(6)
	v_mfma_f32_32x32x16_bf16 v[128:143], v[6:9], v[26:29], v[128:143]
	ds_read_b64_tr_b16 v[26:27], v30 offset:0x1600
	ds_read_b64_tr_b16 v[28:29], v30 offset:0x1e00
	ds_read_b64_tr_b16 v[246:247], v30 offset:0x2600
	ds_read_b64_tr_b16 v[248:249], v30 offset:0x2e00
	ds_read_b64_tr_b16 v[250:251], v30 offset:0x3600
	ds_read_b64_tr_b16 v[252:253], v30 offset:0x3e00
	s_waitcnt lgkmcnt(6)
	v_mfma_f32_32x32x16_bf16 v[128:143], v[10:13], v[144:147], v[128:143]
	s_waitcnt lgkmcnt(6)
	v_mfma_f32_32x32x16_bf16 v[128:143], v[18:21], v[148:151], v[128:143]
	s_waitcnt lgkmcnt(6)
	v_mfma_f32_32x32x16_bf16 v[144:159], v[2:5], v[22:25], v[80:95]
	s_waitcnt lgkmcnt(4)
	v_mfma_f32_32x32x16_bf16 v[144:159], v[6:9], v[26:29], v[144:159]
	s_waitcnt lgkmcnt(2)
	v_mfma_f32_32x32x16_bf16 v[144:159], v[10:13], v[246:249], v[144:159]
	s_waitcnt lgkmcnt(0)
	v_mfma_f32_32x32x16_bf16 v[144:159], v[18:21], v[250:253], v[144:159]

.LBB0_371:
	v_add_f32_e32 v1, v228, v1
	v_add_f32_e32 v1, v231, v1
	v_add_f32_e32 v1, v226, v1
	v_add_f32_e32 v1, v229, v1
	v_add_f32_e32 v1, v225, v1
	v_add_f32_e32 v1, v227, v1
	v_add_f32_e32 v1, v222, v1
	v_add_f32_e32 v1, v224, v1
	v_add_f32_e32 v1, v220, v1
	v_add_f32_e32 v1, v223, v1
	v_add_f32_e32 v1, v218, v1
	v_add_f32_e32 v1, v221, v1
	v_add_f32_e32 v1, v217, v1
	v_add_f32_e32 v1, v219, v1
	v_add_f32_e32 v1, v233, v1
	v_add_f32_e32 v1, v236, v1
	v_add_f32_e32 v1, v237, v1
	v_add_f32_e32 v1, v240, v1
	v_add_f32_e32 v1, v241, v1
	v_add_f32_e32 v1, v243, v1
	v_add_f32_e32 v1, v244, v1
	v_add_f32_e32 v1, v245, v1
	v_add_f32_e32 v1, v213, v1
	v_add_f32_e32 v1, v215, v1
	v_add_f32_e32 v1, v216, v1
	v_add_f32_e32 v1, v234, v1
	v_add_f32_e32 v1, v235, v1
	v_add_f32_e32 v1, v238, v1
	v_add_f32_e32 v1, v239, v1
	v_add_f32_e32 v1, v242, v1
	v_mov_b32_e32 v14, v1
	v_cvt_pk_bf16_f32 v2, v230, v232
	v_cvt_pk_bf16_f32 v3, v228, v231
	v_cvt_pk_bf16_f32 v4, v226, v229
	v_cvt_pk_bf16_f32 v5, v225, v227
	v_cvt_pk_bf16_f32 v6, v222, v224
	v_cvt_pk_bf16_f32 v7, v220, v223
	v_cvt_pk_bf16_f32 v8, v218, v221
	v_cvt_pk_bf16_f32 v9, v217, v219
	v_cvt_pk_bf16_f32 v10, v233, v236
	v_cvt_pk_bf16_f32 v11, v237, v240
	v_cvt_pk_bf16_f32 v12, v241, v243
	v_cvt_pk_bf16_f32 v13, v244, v245
	v_cvt_pk_bf16_f32 v18, v213, v215
	v_cvt_pk_bf16_f32 v19, v216, v234
	v_cvt_pk_bf16_f32 v20, v235, v238
	v_cvt_pk_bf16_f32 v21, v239, v242
	s_nop 1
	v_permlane32_swap_b32_e32 v1, v14
	s_sub_i32 s44, s21, 64
	s_cmp_gt_i32 s44, s6
	s_cbranch_scc1 .LBB0_373
	v_add_u32_e32 v17, s74, v206
	ds_read_b64_tr_b16 v[22:23], v17 offset:0
	ds_read_b64_tr_b16 v[24:25], v17 offset:0x800
	ds_read_b64_tr_b16 v[26:27], v17 offset:0x1000
	ds_read_b64_tr_b16 v[28:29], v17 offset:0x1800
	ds_read_b64_tr_b16 v[128:129], v17 offset:0x2000
	ds_read_b64_tr_b16 v[130:131], v17 offset:0x2800
	ds_read_b64_tr_b16 v[132:133], v17 offset:0x3000
	ds_read_b64_tr_b16 v[134:135], v17 offset:0x3800
	s_waitcnt lgkmcnt(6)
	s_nop 0
	v_mfma_f32_32x32x16_bf16 v[32:47], v[2:5], v[22:25], v[32:47]
	ds_read_b64_tr_b16 v[22:23], v17 offset:0x200
	ds_read_b64_tr_b16 v[24:25], v17 offset:0xa00
	s_waitcnt lgkmcnt(6)
	v_mfma_f32_32x32x16_bf16 v[32:47], v[6:9], v[26:29], v[32:47]
	ds_read_b64_tr_b16 v[26:27], v17 offset:0x1200
	ds_read_b64_tr_b16 v[28:29], v17 offset:0x1a00
	s_waitcnt lgkmcnt(6)
	v_mfma_f32_32x32x16_bf16 v[32:47], v[10:13], v[128:131], v[32:47]
	ds_read_b64_tr_b16 v[128:129], v17 offset:0x2200
	ds_read_b64_tr_b16 v[130:131], v17 offset:0x2a00
	s_waitcnt lgkmcnt(6)
	v_mfma_f32_32x32x16_bf16 v[32:47], v[18:21], v[132:135], v[32:47]
	ds_read_b64_tr_b16 v[132:133], v17 offset:0x3200
	ds_read_b64_tr_b16 v[134:135], v17 offset:0x3a00
	s_waitcnt lgkmcnt(6)
	v_mfma_f32_32x32x16_bf16 v[48:63], v[2:5], v[22:25], v[48:63]
	ds_read_b64_tr_b16 v[22:23], v17 offset:0x400
	ds_read_b64_tr_b16 v[24:25], v17 offset:0xc00
	s_waitcnt lgkmcnt(6)
	v_mfma_f32_32x32x16_bf16 v[48:63], v[6:9], v[26:29], v[48:63]
	ds_read_b64_tr_b16 v[26:27], v17 offset:0x1400
	ds_read_b64_tr_b16 v[28:29], v17 offset:0x1c00
	s_waitcnt lgkmcnt(6)
	v_mfma_f32_32x32x16_bf16 v[48:63], v[10:13], v[128:131], v[48:63]
	ds_read_b64_tr_b16 v[128:129], v17 offset:0x2400
	ds_read_b64_tr_b16 v[130:131], v17 offset:0x2c00
	s_waitcnt lgkmcnt(6)
	v_mfma_f32_32x32x16_bf16 v[48:63], v[18:21], v[132:135], v[48:63]
	ds_read_b64_tr_b16 v[132:133], v17 offset:0x3400
	ds_read_b64_tr_b16 v[134:135], v17 offset:0x3c00
	s_waitcnt lgkmcnt(6)
	v_mfma_f32_32x32x16_bf16 v[64:79], v[2:5], v[22:25], v[64:79]
	ds_read_b64_tr_b16 v[22:23], v17 offset:0x600
	ds_read_b64_tr_b16 v[24:25], v17 offset:0xe00
	s_waitcnt lgkmcnt(6)
	v_mfma_f32_32x32x16_bf16 v[64:79], v[6:9], v[26:29], v[64:79]
	ds_read_b64_tr_b16 v[26:27], v17 offset:0x1600
	ds_read_b64_tr_b16 v[28:29], v17 offset:0x1e00
	s_waitcnt lgkmcnt(6)
	v_mfma_f32_32x32x16_bf16 v[64:79], v[10:13], v[128:131], v[64:79]
	ds_read_b64_tr_b16 v[128:129], v17 offset:0x2600
	ds_read_b64_tr_b16 v[130:131], v17 offset:0x2e00
	s_waitcnt lgkmcnt(6)
	v_mfma_f32_32x32x16_bf16 v[64:79], v[18:21], v[132:135], v[64:79]
	ds_read_b64_tr_b16 v[132:133], v17 offset:0x3600
	ds_read_b64_tr_b16 v[134:135], v17 offset:0x3e00
	s_waitcnt lgkmcnt(6)
	v_mfma_f32_32x32x16_bf16 v[80:95], v[2:5], v[22:25], v[80:95]
	s_waitcnt lgkmcnt(4)
	v_mfma_f32_32x32x16_bf16 v[80:95], v[6:9], v[26:29], v[80:95]
	s_waitcnt lgkmcnt(2)
	v_mfma_f32_32x32x16_bf16 v[80:95], v[10:13], v[128:131], v[80:95]
	s_waitcnt lgkmcnt(0)
	v_mfma_f32_32x32x16_bf16 v[80:95], v[18:21], v[132:135], v[80:95]

.LBB0_380:
	v_cndmask_b32_e64 v2, v2, v214, s[4:5]
	v_mul_f32_e32 v2, 0xbe0293ee, v2
	v_fmamk_f32 v3, v112, 0x3e0293ee, v2
	v_fmamk_f32 v4, v113, 0x3e0293ee, v2
	v_exp_f32_e32 v3, v3
	v_fmamk_f32 v5, v114, 0x3e0293ee, v2
	v_exp_f32_e32 v4, v4
	v_fmamk_f32 v6, v115, 0x3e0293ee, v2
	v_exp_f32_e32 v5, v5
	v_fmamk_f32 v7, v116, 0x3e0293ee, v2
	v_fmamk_f32 v8, v117, 0x3e0293ee, v2
	v_fmamk_f32 v9, v118, 0x3e0293ee, v2
	v_fmamk_f32 v10, v119, 0x3e0293ee, v2
	v_fmamk_f32 v11, v120, 0x3e0293ee, v2
	v_fmamk_f32 v12, v121, 0x3e0293ee, v2
	v_fmamk_f32 v13, v122, 0x3e0293ee, v2
	v_fmamk_f32 v18, v123, 0x3e0293ee, v2
	v_fmamk_f32 v19, v124, 0x3e0293ee, v2
	v_fmamk_f32 v20, v125, 0x3e0293ee, v2
	v_fmamk_f32 v21, v126, 0x3e0293ee, v2
	v_fmamk_f32 v22, v127, 0x3e0293ee, v2
	v_fmamk_f32 v23, v96, 0x3e0293ee, v2
	v_fmamk_f32 v24, v97, 0x3e0293ee, v2
	v_fmamk_f32 v25, v98, 0x3e0293ee, v2
	v_fmamk_f32 v26, v99, 0x3e0293ee, v2
	v_fmamk_f32 v27, v100, 0x3e0293ee, v2
	v_fmamk_f32 v28, v101, 0x3e0293ee, v2
	v_fmamk_f32 v29, v102, 0x3e0293ee, v2
	v_fmamk_f32 v30, v103, 0x3e0293ee, v2
	v_fmamk_f32 v31, v104, 0x3e0293ee, v2
	v_fmamk_f32 v96, v105, 0x3e0293ee, v2
	v_fmamk_f32 v97, v106, 0x3e0293ee, v2
	v_fmamk_f32 v98, v107, 0x3e0293ee, v2
	v_fmamk_f32 v99, v108, 0x3e0293ee, v2
	v_fmamk_f32 v100, v109, 0x3e0293ee, v2
	v_fmamk_f32 v101, v110, 0x3e0293ee, v2
	v_fmac_f32_e32 v2, 0x3e0293ee, v111
	v_exp_f32_e32 v6, v6
	v_exp_f32_e32 v7, v7
	v_exp_f32_e32 v104, v2
	v_add_f32_e32 v2, 0, v3
	v_exp_f32_e32 v8, v8
	v_add_f32_e32 v2, v4, v2
	v_exp_f32_e32 v9, v9
	v_add_f32_e32 v2, v5, v2
	v_exp_f32_e32 v10, v10
	v_add_f32_e32 v2, v6, v2
	v_exp_f32_e32 v11, v11
	v_add_f32_e32 v2, v7, v2
	v_exp_f32_e32 v12, v12
	v_add_f32_e32 v2, v8, v2
	v_exp_f32_e32 v13, v13
	v_add_f32_e32 v2, v9, v2
	v_exp_f32_e32 v18, v18
	v_add_f32_e32 v2, v10, v2
	v_exp_f32_e32 v19, v19
	v_add_f32_e32 v2, v11, v2
	v_exp_f32_e32 v20, v20
	v_add_f32_e32 v2, v12, v2
	v_exp_f32_e32 v21, v21
	v_add_f32_e32 v2, v13, v2
	v_exp_f32_e32 v102, v22
	v_add_f32_e32 v2, v18, v2
	v_exp_f32_e32 v103, v23
	v_add_f32_e32 v2, v19, v2
	v_exp_f32_e32 v24, v24
	v_add_f32_e32 v2, v20, v2
	v_exp_f32_e32 v25, v25
	v_add_f32_e32 v2, v21, v2
	v_exp_f32_e32 v26, v26
	v_add_f32_e32 v2, v102, v2
	v_exp_f32_e32 v27, v27
	v_add_f32_e32 v2, v103, v2
	v_exp_f32_e32 v28, v28
	v_add_f32_e32 v2, v24, v2
	v_exp_f32_e32 v29, v29
	v_add_f32_e32 v2, v25, v2
	v_exp_f32_e32 v30, v30
	v_add_f32_e32 v2, v26, v2
	v_exp_f32_e32 v31, v31
	v_add_f32_e32 v2, v27, v2
	v_exp_f32_e32 v96, v96
	v_add_f32_e32 v2, v28, v2
	v_exp_f32_e32 v97, v97
	v_add_f32_e32 v2, v29, v2
	v_exp_f32_e32 v98, v98
	v_add_f32_e32 v2, v30, v2
	v_exp_f32_e32 v99, v99
	v_add_f32_e32 v2, v31, v2
	v_exp_f32_e32 v100, v100
	v_add_f32_e32 v2, v96, v2
	v_exp_f32_e32 v101, v101
	v_add_f32_e32 v2, v97, v2
	v_add_f32_e32 v2, v98, v2
	v_add_f32_e32 v2, v99, v2
	v_add_f32_e32 v2, v100, v2
	v_add_f32_e32 v2, v101, v2
	s_waitcnt vmcnt(0) lgkmcnt(0)
	s_barrier
	v_add_f32_e32 v22, v104, v2
	v_mov_b32_e32 v23, v22
	v_cvt_pk_bf16_f32 v2, v3, v4
	v_cvt_pk_bf16_f32 v3, v5, v6
	v_cvt_pk_bf16_f32 v4, v7, v8
	v_cvt_pk_bf16_f32 v5, v9, v10
	v_cvt_pk_bf16_f32 v6, v11, v12
	v_cvt_pk_bf16_f32 v7, v13, v18
	v_cvt_pk_bf16_f32 v8, v19, v20
	v_cvt_pk_bf16_f32 v9, v21, v102
	v_cvt_pk_bf16_f32 v10, v103, v24
	v_cvt_pk_bf16_f32 v11, v25, v26
	v_cvt_pk_bf16_f32 v12, v27, v28
	v_cvt_pk_bf16_f32 v13, v29, v30
	v_cvt_pk_bf16_f32 v18, v31, v96
	v_cvt_pk_bf16_f32 v19, v97, v98
	v_cvt_pk_bf16_f32 v20, v99, v100
	v_cvt_pk_bf16_f32 v21, v101, v104
	s_nop 1
	v_permlane32_swap_b32_e32 v22, v23
	s_and_b64 vcc, exec, s[2:3]
	s_cbranch_vccnz .LBB0_382
	v_add_u32_e32 v104, s87, v206
	ds_read_b64_tr_b16 v[24:25], v104 offset:0
	ds_read_b64_tr_b16 v[26:27], v104 offset:0x800
	ds_read_b64_tr_b16 v[28:29], v104 offset:0x1000
	ds_read_b64_tr_b16 v[30:31], v104 offset:0x1800
	ds_read_b64_tr_b16 v[96:97], v104 offset:0x2000
	ds_read_b64_tr_b16 v[98:99], v104 offset:0x2800
	ds_read_b64_tr_b16 v[100:101], v104 offset:0x3000
	ds_read_b64_tr_b16 v[102:103], v104 offset:0x3800
	s_waitcnt lgkmcnt(6)
	s_nop 0
	v_mfma_f32_32x32x16_bf16 v[32:47], v[2:5], v[24:27], v[32:47]
	ds_read_b64_tr_b16 v[24:25], v104 offset:0x200
	ds_read_b64_tr_b16 v[26:27], v104 offset:0xa00
	s_waitcnt lgkmcnt(6)
	v_mfma_f32_32x32x16_bf16 v[32:47], v[6:9], v[28:31], v[32:47]
	ds_read_b64_tr_b16 v[28:29], v104 offset:0x1200
	ds_read_b64_tr_b16 v[30:31], v104 offset:0x1a00
	s_waitcnt lgkmcnt(6)
	v_mfma_f32_32x32x16_bf16 v[32:47], v[10:13], v[96:99], v[32:47]
	ds_read_b64_tr_b16 v[96:97], v104 offset:0x2200
	ds_read_b64_tr_b16 v[98:99], v104 offset:0x2a00
	s_waitcnt lgkmcnt(6)
	v_mfma_f32_32x32x16_bf16 v[32:47], v[18:21], v[100:103], v[32:47]
	ds_read_b64_tr_b16 v[100:101], v104 offset:0x3200
	ds_read_b64_tr_b16 v[102:103], v104 offset:0x3a00
	s_waitcnt lgkmcnt(6)
	v_mfma_f32_32x32x16_bf16 v[48:63], v[2:5], v[24:27], v[48:63]
	ds_read_b64_tr_b16 v[24:25], v104 offset:0x400
	ds_read_b64_tr_b16 v[26:27], v104 offset:0xc00
	s_waitcnt lgkmcnt(6)
	v_mfma_f32_32x32x16_bf16 v[48:63], v[6:9], v[28:31], v[48:63]
	ds_read_b64_tr_b16 v[28:29], v104 offset:0x1400
	ds_read_b64_tr_b16 v[30:31], v104 offset:0x1c00
	s_waitcnt lgkmcnt(6)
	v_mfma_f32_32x32x16_bf16 v[48:63], v[10:13], v[96:99], v[48:63]
	ds_read_b64_tr_b16 v[96:97], v104 offset:0x2400
	ds_read_b64_tr_b16 v[98:99], v104 offset:0x2c00
	s_waitcnt lgkmcnt(6)
	v_mfma_f32_32x32x16_bf16 v[48:63], v[18:21], v[100:103], v[48:63]
	ds_read_b64_tr_b16 v[100:101], v104 offset:0x3400
	ds_read_b64_tr_b16 v[102:103], v104 offset:0x3c00
	s_waitcnt lgkmcnt(6)
	v_mfma_f32_32x32x16_bf16 v[64:79], v[2:5], v[24:27], v[64:79]
	ds_read_b64_tr_b16 v[24:25], v104 offset:0x600
	ds_read_b64_tr_b16 v[26:27], v104 offset:0xe00
	s_waitcnt lgkmcnt(6)
	v_mfma_f32_32x32x16_bf16 v[64:79], v[6:9], v[28:31], v[64:79]
	ds_read_b64_tr_b16 v[28:29], v104 offset:0x1600
	ds_read_b64_tr_b16 v[30:31], v104 offset:0x1e00
	s_waitcnt lgkmcnt(6)
	v_mfma_f32_32x32x16_bf16 v[64:79], v[10:13], v[96:99], v[64:79]
	ds_read_b64_tr_b16 v[96:97], v104 offset:0x2600
	ds_read_b64_tr_b16 v[98:99], v104 offset:0x2e00
	s_waitcnt lgkmcnt(6)
	v_mfma_f32_32x32x16_bf16 v[64:79], v[18:21], v[100:103], v[64:79]
	ds_read_b64_tr_b16 v[100:101], v104 offset:0x3600
	ds_read_b64_tr_b16 v[102:103], v104 offset:0x3e00
	s_waitcnt lgkmcnt(6)
	v_mfma_f32_32x32x16_bf16 v[80:95], v[2:5], v[24:27], v[80:95]
	s_waitcnt lgkmcnt(4)
	v_mfma_f32_32x32x16_bf16 v[80:95], v[6:9], v[28:31], v[80:95]
	s_waitcnt lgkmcnt(2)
	v_mfma_f32_32x32x16_bf16 v[80:95], v[10:13], v[96:99], v[80:95]
	s_waitcnt lgkmcnt(0)
	v_mfma_f32_32x32x16_bf16 v[80:95], v[18:21], v[100:103], v[80:95]

.LBB0_1169:
	s_mov_b32 s61, s53
	s_mov_b32 s53, s65
	s_ashr_i32 s65, s64, 31
	s_lshl_b64 s[66:67], s[64:65], 14
	s_add_u32 s8, s54, s66
	s_addc_u32 s9, s55, s67
	s_add_i32 s70, s53, s90
	s_mov_b32 s71, m0
	s_mov_b32 m0, s70
	s_nop 0
	global_load_lds_dwordx4 v183, s[8:9]
	s_mov_b32 m0, s71
	s_addk_i32 s70, 0x400
	s_mov_b32 s71, m0
	s_mov_b32 m0, s70
	s_nop 0
	global_load_lds_dwordx4 v184, s[8:9]
	s_mov_b32 m0, s71
	s_lshl_b64 s[8:9], s[64:65], 8
	s_add_u32 s8, s58, s8
	s_addc_u32 s9, s59, s9
	s_ashr_i32 s65, s53, 6
	s_cmp_lg_u32 0, -1
	s_cselect_b32 s70, 0, 0
	s_add_i32 s65, s70, s65
	s_add_i32 s65, s65, 0x18800
	s_mov_b32 s70, m0
	s_mov_b32 m0, s65
	s_nop 0
	global_load_lds_dword v185, s[8:9]
	s_mov_b32 m0, s70
	s_add_i32 s8, s64, 1
	s_ashr_i32 s9, s8, 31
	s_lshl_b64 s[8:9], s[8:9], 14
	s_add_u32 s8, s56, s8
	s_addc_u32 s9, s57, s9
	s_add_i32 s65, s68, s83
	s_mov_b32 s70, m0
	s_mov_b32 m0, s65
	s_nop 0
	global_load_lds_dwordx4 v187, s[8:9]
	s_mov_b32 m0, s70
	s_addk_i32 s65, 0x400
	s_mov_b32 s70, m0
	s_mov_b32 m0, s65
	s_nop 0
	global_load_lds_dwordx4 v186, s[8:9]
	s_mov_b32 m0, s70
	s_ashr_i32 s8, s61, 8
	v_lshl_add_u32 v1, s8, 2, v128
	ds_read_b128 v[96:99], v1
	ds_read_b128 v[100:103], v1 offset:32
	ds_read_b128 v[80:83], v1 offset:128
	ds_read_b128 v[84:87], v1 offset:160
	ds_read_b128 v[104:107], v1 offset:64
	ds_read_b128 v[108:111], v1 offset:96
	ds_read_b128 v[88:91], v1 offset:192
	ds_read_b128 v[92:95], v1 offset:224
	s_add_i32 s8, s61, 0
	v_add3_u32 v1, s8, v197, v196
	v_add3_u32 v6, s8, v198, v196
	v_add3_u32 v7, s8, v199, v196
	v_add3_u32 v8, s8, v200, v196
	s_setprio 1
	ds_read_b128 v[2:5], v1 offset:49152
	ds_read_b128 v[220:223], v1 offset:57344
	ds_read_b128 v[224:227], v6 offset:49152
	ds_read_b128 v[228:231], v6 offset:57344
	ds_read_b128 v[232:235], v7 offset:49152
	s_waitcnt lgkmcnt(4)
	v_mfma_f32_32x32x16_bf16 v[96:111], v[2:5], v[172:175], v[96:111]
	ds_read_b128 v[2:5], v7 offset:57344
	s_waitcnt lgkmcnt(4)
	v_mfma_f32_32x32x16_bf16 v[80:95], v[220:223], v[172:175], v[80:95]
	ds_read_b128 v[220:223], v8 offset:49152
	s_waitcnt lgkmcnt(4)
	v_mfma_f32_32x32x16_bf16 v[96:111], v[224:227], v[168:171], v[96:111]
	ds_read_b128 v[224:227], v8 offset:57344
	s_waitcnt lgkmcnt(4)
	v_mfma_f32_32x32x16_bf16 v[80:95], v[228:231], v[168:171], v[80:95]
	ds_read_b128 v[228:231], v1 offset:49280
	s_waitcnt lgkmcnt(4)
	v_mfma_f32_32x32x16_bf16 v[96:111], v[232:235], v[164:167], v[96:111]
	ds_read_b128 v[232:235], v1 offset:57472
	s_waitcnt lgkmcnt(4)
	v_mfma_f32_32x32x16_bf16 v[80:95], v[2:5], v[164:167], v[80:95]
	ds_read_b128 v[2:5], v6 offset:49280
	s_waitcnt lgkmcnt(4)
	v_mfma_f32_32x32x16_bf16 v[96:111], v[220:223], v[160:163], v[96:111]
	ds_read_b128 v[220:223], v6 offset:57472
	s_waitcnt lgkmcnt(4)
	v_mfma_f32_32x32x16_bf16 v[80:95], v[224:227], v[160:163], v[80:95]
	ds_read_b128 v[224:227], v7 offset:49280
	s_waitcnt lgkmcnt(4)
	v_mfma_f32_32x32x16_bf16 v[96:111], v[228:231], v[156:159], v[96:111]
	ds_read_b128 v[228:231], v7 offset:57472
	s_waitcnt lgkmcnt(4)
	v_mfma_f32_32x32x16_bf16 v[80:95], v[232:235], v[156:159], v[80:95]
	ds_read_b128 v[232:235], v8 offset:49280
	s_waitcnt lgkmcnt(4)
	v_mfma_f32_32x32x16_bf16 v[96:111], v[2:5], v[152:155], v[96:111]
	ds_read_b128 v[2:5], v8 offset:57472
	s_waitcnt lgkmcnt(4)
	v_mfma_f32_32x32x16_bf16 v[80:95], v[220:223], v[152:155], v[80:95]
	s_waitcnt lgkmcnt(3)
	v_mfma_f32_32x32x16_bf16 v[96:111], v[224:227], v[148:151], v[96:111]
	s_waitcnt lgkmcnt(2)
	v_mfma_f32_32x32x16_bf16 v[80:95], v[228:231], v[148:151], v[80:95]
	s_waitcnt lgkmcnt(1)
	v_mfma_f32_32x32x16_bf16 v[96:111], v[232:235], v[144:147], v[96:111]
	s_waitcnt lgkmcnt(0)
	v_mfma_f32_32x32x16_bf16 v[80:95], v[2:5], v[144:147], v[80:95]
	s_setprio 0
	v_add_f32_e32 v1, 0, v215
	v_add_f32_e32 v1, v217, v1
	v_add_f32_e32 v1, v213, v1
	v_add_f32_e32 v1, v216, v1
	v_add_f32_e32 v1, v211, v1
	v_add_f32_e32 v1, v214, v1
	v_add_f32_e32 v1, v210, v1
	v_add_f32_e32 v1, v212, v1
	v_add_f32_e32 v1, v205, v1
	v_add_f32_e32 v1, v208, v1
	v_add_f32_e32 v1, v203, v1
	v_add_f32_e32 v1, v206, v1
	v_exp_f32_e32 v2, v126
	v_add_f32_e32 v1, v202, v1
	v_exp_f32_e32 v12, v127
	v_add_f32_e32 v1, v209, v1
	v_exp_f32_e32 v13, v124
	v_add_f32_e32 v1, v204, v1
	v_exp_f32_e32 v14, v125
	v_add_f32_e32 v1, v207, v1
	v_exp_f32_e32 v15, v122
	v_add_f32_e32 v1, v2, v1
	v_exp_f32_e32 v122, v123
	v_add_f32_e32 v1, v12, v1
	v_exp_f32_e32 v120, v120
	v_add_f32_e32 v1, v13, v1
	v_exp_f32_e32 v121, v121
	v_add_f32_e32 v1, v14, v1
	v_exp_f32_e32 v118, v118
	v_add_f32_e32 v1, v15, v1
	v_exp_f32_e32 v119, v119
	v_add_f32_e32 v1, v122, v1
	v_exp_f32_e32 v116, v116
	v_add_f32_e32 v1, v120, v1
	v_exp_f32_e32 v117, v117
	v_add_f32_e32 v1, v121, v1
	v_exp_f32_e32 v114, v114
	v_add_f32_e32 v1, v118, v1
	v_exp_f32_e32 v115, v115
	v_add_f32_e32 v1, v119, v1
	v_exp_f32_e32 v123, v112
	v_add_f32_e32 v1, v116, v1
	v_exp_f32_e32 v124, v113
	v_add_f32_e32 v1, v117, v1
	v_add_f32_e32 v1, v114, v1
	v_add_f32_e32 v1, v115, v1
	v_add_f32_e32 v1, v123, v1
	v_add_f32_e32 v1, v124, v1
	v_mov_b32_e32 v3, v1
	s_nop 1
	v_permlane32_swap_b32_e32 v1, v3
	v_cvt_pk_bf16_f32 v4, v215, v217
	v_cvt_pk_bf16_f32 v5, v213, v216
	v_cvt_pk_bf16_f32 v6, v211, v214
	v_cvt_pk_bf16_f32 v7, v210, v212
	v_cvt_pk_bf16_f32 v8, v205, v208
	v_cvt_pk_bf16_f32 v9, v203, v206
	v_cvt_pk_bf16_f32 v10, v202, v209
	v_cvt_pk_bf16_f32 v11, v204, v207
	v_cvt_pk_bf16_f32 v12, v2, v12
	v_cvt_pk_bf16_f32 v13, v13, v14
	v_cvt_pk_bf16_f32 v14, v15, v122
	v_cvt_pk_bf16_f32 v15, v120, v121
	v_cvt_pk_bf16_f32 v112, v118, v119
	v_cvt_pk_bf16_f32 v113, v116, v117
	v_cvt_pk_bf16_f32 v114, v114, v115
	v_cvt_pk_bf16_f32 v115, v123, v124
	s_nop 0
	v_permlane32_swap_b32_e32 v4, v6
	v_permlane32_swap_b32_e32 v5, v7
	v_permlane32_swap_b32_e32 v8, v10
	v_permlane32_swap_b32_e32 v9, v11
	v_permlane32_swap_b32_e32 v12, v14
	v_permlane32_swap_b32_e32 v13, v15
	v_permlane32_swap_b32_e32 v112, v114
	v_permlane32_swap_b32_e32 v113, v115
	v_add_u32_e32 v2, s53, v193
	ds_read_b64_tr_b16 v[116:117], v2 offset:0
	ds_read_b64_tr_b16 v[118:119], v2 offset:0x800
	ds_read_b64_tr_b16 v[120:121], v2 offset:0x1000
	ds_read_b64_tr_b16 v[122:123], v2 offset:0x1800
	ds_read_b64_tr_b16 v[124:125], v2 offset:0x2000
	ds_read_b64_tr_b16 v[126:127], v2 offset:0x2800
	ds_read_b64_tr_b16 v[132:133], v2 offset:0x3000
	ds_read_b64_tr_b16 v[134:135], v2 offset:0x3800
	s_waitcnt lgkmcnt(6)
	s_nop 0
	v_mfma_f32_32x32x16_bf16 v[16:31], v[4:7], v[116:119], v[16:31]
	ds_read_b64_tr_b16 v[116:117], v2 offset:0x200
	ds_read_b64_tr_b16 v[118:119], v2 offset:0xa00
	s_waitcnt lgkmcnt(6)
	v_mfma_f32_32x32x16_bf16 v[16:31], v[8:11], v[120:123], v[16:31]
	ds_read_b64_tr_b16 v[120:121], v2 offset:0x1200
	ds_read_b64_tr_b16 v[122:123], v2 offset:0x1a00
	s_waitcnt lgkmcnt(6)
	v_mfma_f32_32x32x16_bf16 v[16:31], v[12:15], v[124:127], v[16:31]
	ds_read_b64_tr_b16 v[124:125], v2 offset:0x2200
	ds_read_b64_tr_b16 v[126:127], v2 offset:0x2a00
	s_waitcnt lgkmcnt(6)
	v_mfma_f32_32x32x16_bf16 v[16:31], v[112:115], v[132:135], v[16:31]
	ds_read_b64_tr_b16 v[132:133], v2 offset:0x3200
	ds_read_b64_tr_b16 v[134:135], v2 offset:0x3a00
	s_waitcnt lgkmcnt(6)
	v_mfma_f32_32x32x16_bf16 v[48:63], v[4:7], v[116:119], v[48:63]
	ds_read_b64_tr_b16 v[116:117], v2 offset:0x400
	ds_read_b64_tr_b16 v[118:119], v2 offset:0xc00
	s_waitcnt lgkmcnt(6)
	v_mfma_f32_32x32x16_bf16 v[48:63], v[8:11], v[120:123], v[48:63]
	ds_read_b64_tr_b16 v[120:121], v2 offset:0x1400
	ds_read_b64_tr_b16 v[122:123], v2 offset:0x1c00
	s_waitcnt lgkmcnt(6)
	v_mfma_f32_32x32x16_bf16 v[48:63], v[12:15], v[124:127], v[48:63]
	ds_read_b64_tr_b16 v[124:125], v2 offset:0x2400
	ds_read_b64_tr_b16 v[126:127], v2 offset:0x2c00
	s_waitcnt lgkmcnt(6)
	v_mfma_f32_32x32x16_bf16 v[48:63], v[112:115], v[132:135], v[48:63]
	ds_read_b64_tr_b16 v[132:133], v2 offset:0x3400
	ds_read_b64_tr_b16 v[134:135], v2 offset:0x3c00
	s_waitcnt lgkmcnt(6)
	v_mfma_f32_32x32x16_bf16 v[64:79], v[4:7], v[116:119], v[64:79]
	ds_read_b64_tr_b16 v[116:117], v2 offset:0x600
	ds_read_b64_tr_b16 v[118:119], v2 offset:0xe00
	s_waitcnt lgkmcnt(6)
	v_mfma_f32_32x32x16_bf16 v[64:79], v[8:11], v[120:123], v[64:79]
	ds_read_b64_tr_b16 v[120:121], v2 offset:0x1600
	ds_read_b64_tr_b16 v[122:123], v2 offset:0x1e00
	s_waitcnt lgkmcnt(6)
	v_mfma_f32_32x32x16_bf16 v[64:79], v[12:15], v[124:127], v[64:79]
	ds_read_b64_tr_b16 v[124:125], v2 offset:0x2600
	ds_read_b64_tr_b16 v[126:127], v2 offset:0x2e00
	s_waitcnt lgkmcnt(6)
	v_mfma_f32_32x32x16_bf16 v[64:79], v[112:115], v[132:135], v[64:79]
	ds_read_b64_tr_b16 v[132:133], v2 offset:0x3600
	ds_read_b64_tr_b16 v[134:135], v2 offset:0x3e00
	s_waitcnt lgkmcnt(6)
	v_mfma_f32_32x32x16_bf16 v[32:47], v[4:7], v[116:119], v[32:47]
	s_add_i32 s8, s91, 64
	s_cmp_le_i32 s8, s69
	s_waitcnt lgkmcnt(4)
	v_mfma_f32_32x32x16_bf16 v[32:47], v[8:11], v[120:123], v[32:47]
	s_waitcnt lgkmcnt(2)
	v_mfma_f32_32x32x16_bf16 v[32:47], v[12:15], v[124:127], v[32:47]
	s_waitcnt lgkmcnt(0)
	v_mfma_f32_32x32x16_bf16 v[32:47], v[112:115], v[132:135], v[32:47]
	s_cbranch_scc1 .LBB0_1171
	v_add_u32_e32 v2, 0x4000003b, v130
	v_cmp_gt_u32_e32 vcc, 2.0, v2
	v_add_u32_e32 v2, 27, v130
	s_nop 0
	v_cndmask_b32_e32 v96, v179, v96, vcc
	v_cmp_lt_u32_e32 vcc, s96, v2
	v_add_u32_e32 v2, 58, v130
	s_nop 0
	v_cndmask_b32_e32 v80, v179, v80, vcc
	v_cmp_lt_u32_e32 vcc, s96, v2
	v_add_u32_e32 v2, 26, v130
	s_nop 0
	v_cndmask_b32_e32 v97, v179, v97, vcc
	v_cmp_lt_u32_e32 vcc, s96, v2
	v_add_u32_e32 v2, 57, v130
	s_nop 0
	v_cndmask_b32_e32 v81, v179, v81, vcc
	v_cmp_lt_u32_e32 vcc, s96, v2
	v_add_u32_e32 v2, 25, v130
	s_nop 0
	v_cndmask_b32_e32 v98, v179, v98, vcc
	v_cmp_lt_u32_e32 vcc, s96, v2
	v_add_u32_e32 v2, 56, v130
	s_nop 0
	v_cndmask_b32_e32 v82, v179, v82, vcc
	v_cmp_lt_u32_e32 vcc, s96, v2
	v_add_u32_e32 v2, 24, v130
	s_nop 0
	v_cndmask_b32_e32 v99, v179, v99, vcc
	v_cmp_lt_u32_e32 vcc, s96, v2
	v_add_u32_e32 v2, 51, v130
	s_nop 0
	v_cndmask_b32_e32 v83, v179, v83, vcc
	v_cmp_lt_u32_e32 vcc, s96, v2
	v_add_u32_e32 v2, 19, v130
	s_nop 0
	v_cndmask_b32_e32 v100, v179, v100, vcc
	v_cmp_lt_u32_e32 vcc, s96, v2
	v_add_u32_e32 v2, 50, v130
	s_nop 0
	v_cndmask_b32_e32 v84, v179, v84, vcc
	v_cmp_lt_u32_e32 vcc, s96, v2
	v_add_u32_e32 v2, 18, v130
	s_nop 0
	v_cndmask_b32_e32 v101, v179, v101, vcc
	v_cmp_lt_u32_e32 vcc, s96, v2
	v_add_u32_e32 v2, 49, v130
	s_nop 0
	v_cndmask_b32_e32 v85, v179, v85, vcc
	v_cmp_lt_u32_e32 vcc, s96, v2
	v_add_u32_e32 v2, 17, v130
	s_nop 0
	v_cndmask_b32_e32 v102, v179, v102, vcc
	v_cmp_lt_u32_e32 vcc, s96, v2
	v_add_u32_e32 v2, 48, v130
	s_nop 0
	v_cndmask_b32_e32 v86, v179, v86, vcc
	v_cmp_lt_u32_e32 vcc, s96, v2
	v_add_u32_e32 v2, 16, v130
	s_nop 0
	v_cndmask_b32_e32 v103, v179, v103, vcc
	v_cmp_lt_u32_e32 vcc, s96, v2
	v_add_u32_e32 v2, 43, v130
	s_nop 0
	v_cndmask_b32_e32 v87, v179, v87, vcc
	v_cmp_lt_u32_e32 vcc, s96, v2
	v_add_u32_e32 v2, 11, v130
	s_nop 0
	v_cndmask_b32_e32 v104, v179, v104, vcc
	v_cmp_lt_u32_e32 vcc, s96, v2
	v_add_u32_e32 v2, 42, v130
	s_nop 0
	v_cndmask_b32_e32 v88, v179, v88, vcc
	v_cmp_lt_u32_e32 vcc, s96, v2
	v_add_u32_e32 v2, 10, v130
	s_nop 0
	v_cndmask_b32_e32 v105, v179, v105, vcc
	v_cmp_lt_u32_e32 vcc, s96, v2
	v_add_u32_e32 v2, 41, v130
	s_nop 0
	v_cndmask_b32_e32 v89, v179, v89, vcc
	v_cmp_lt_u32_e32 vcc, s96, v2
	v_add_u32_e32 v2, 9, v130
	s_nop 0
	v_cndmask_b32_e32 v106, v179, v106, vcc
	v_cmp_lt_u32_e32 vcc, s96, v2
	v_add_u32_e32 v2, 40, v130
	s_nop 0
	v_cndmask_b32_e32 v90, v179, v90, vcc
	v_cmp_lt_u32_e32 vcc, s96, v2
	v_add_u32_e32 v2, 8, v130
	s_nop 0
	v_cndmask_b32_e32 v107, v179, v107, vcc
	v_cmp_lt_u32_e32 vcc, s96, v2
	v_add_u32_e32 v2, 35, v130
	s_nop 0
	v_cndmask_b32_e32 v91, v179, v91, vcc
	v_cmp_lt_u32_e32 vcc, s96, v2
	v_add_u32_e32 v2, 3, v130
	s_nop 0
	v_cndmask_b32_e32 v108, v179, v108, vcc
	v_cmp_lt_u32_e32 vcc, s96, v2
	v_add_u32_e32 v2, 34, v130
	s_nop 0
	v_cndmask_b32_e32 v92, v179, v92, vcc
	v_cmp_lt_u32_e32 vcc, s96, v2
	v_add_u32_e32 v2, 2, v130
	s_nop 0
	v_cndmask_b32_e32 v109, v179, v109, vcc
	v_cmp_lt_u32_e32 vcc, s96, v2
	v_add_u32_e32 v2, 33, v130
	s_nop 0
	v_cndmask_b32_e32 v93, v179, v93, vcc
	v_cmp_lt_u32_e32 vcc, s96, v2
	v_add_u32_e32 v2, 1, v130
	s_nop 0
	v_cndmask_b32_e32 v110, v179, v110, vcc
	v_cmp_lt_u32_e32 vcc, s96, v2
	v_add_u32_e32 v2, 32, v130
	s_nop 0
	v_cndmask_b32_e32 v94, v179, v94, vcc
	v_cmp_lt_u32_e32 vcc, s96, v2
	s_nop 1
	v_cndmask_b32_e32 v111, v179, v111, vcc
	v_cmp_lt_u32_e32 vcc, s96, v130
	s_nop 1
	v_cndmask_b32_e32 v95, v179, v95, vcc

.LBB0_1175:
	v_cndmask_b32_e64 v2, v2, v201, s[8:9]
	s_waitcnt vmcnt(5) lgkmcnt(0)
	s_barrier
	s_add_i32 s8, s61, s90
	s_mov_b32 s9, m0
	s_mov_b32 m0, s8
	s_nop 0
	global_load_lds_dwordx4 v183, s[62:63]
	s_mov_b32 m0, s9
	s_addk_i32 s8, 0x400
	s_mov_b32 s9, m0
	s_mov_b32 m0, s8
	s_nop 0
	global_load_lds_dwordx4 v184, s[62:63]
	s_mov_b32 m0, s9
	s_ashr_i32 s8, s61, 6
	s_cmp_lg_u32 0, -1
	s_cselect_b32 s9, 0, 0
	s_add_i32 s8, s9, s8
	s_add_i32 s8, s8, 0x18800
	s_mov_b32 s9, m0
	s_mov_b32 m0, s8
	s_nop 0
	global_load_lds_dword v185, s[0:1]
	s_mov_b32 m0, s9
	s_add_u32 s8, s56, s66
	s_addc_u32 s9, s57, s67
	s_add_i32 s65, s53, s83
	s_mov_b32 s66, m0
	s_mov_b32 m0, s65
	s_nop 0
	global_load_lds_dwordx4 v187, s[8:9]
	s_mov_b32 m0, s66
	s_addk_i32 s65, 0x400
	s_mov_b32 s66, m0
	s_mov_b32 m0, s65
	s_nop 0
	global_load_lds_dwordx4 v186, s[8:9]
	s_mov_b32 m0, s66
	v_mul_f32_e32 v5, 0xbe0293ee, v2
	v_fmamk_f32 v6, v96, 0x3e0293ee, v5
	v_fmamk_f32 v7, v97, 0x3e0293ee, v5
	v_fmamk_f32 v8, v98, 0x3e0293ee, v5
	v_fmamk_f32 v9, v99, 0x3e0293ee, v5
	v_fmamk_f32 v10, v100, 0x3e0293ee, v5
	v_fmamk_f32 v11, v101, 0x3e0293ee, v5
	v_fmamk_f32 v12, v102, 0x3e0293ee, v5
	v_fmamk_f32 v13, v103, 0x3e0293ee, v5
	v_fmamk_f32 v14, v104, 0x3e0293ee, v5
	v_fmamk_f32 v15, v105, 0x3e0293ee, v5
	v_fmamk_f32 v96, v106, 0x3e0293ee, v5
	v_fmamk_f32 v97, v107, 0x3e0293ee, v5
	v_fmamk_f32 v98, v108, 0x3e0293ee, v5
	v_fmamk_f32 v99, v109, 0x3e0293ee, v5
	v_fmamk_f32 v100, v110, 0x3e0293ee, v5
	v_fmamk_f32 v101, v111, 0x3e0293ee, v5
	v_fmamk_f32 v112, v80, 0x3e0293ee, v5
	v_fmamk_f32 v113, v81, 0x3e0293ee, v5
	v_fmamk_f32 v114, v82, 0x3e0293ee, v5
	v_fmamk_f32 v115, v83, 0x3e0293ee, v5
	v_fmamk_f32 v116, v84, 0x3e0293ee, v5
	v_fmamk_f32 v117, v85, 0x3e0293ee, v5
	v_fmamk_f32 v118, v86, 0x3e0293ee, v5
	v_fmamk_f32 v119, v87, 0x3e0293ee, v5
	v_fmamk_f32 v120, v88, 0x3e0293ee, v5
	v_fmamk_f32 v121, v89, 0x3e0293ee, v5
	v_fmamk_f32 v122, v90, 0x3e0293ee, v5
	v_fmamk_f32 v123, v91, 0x3e0293ee, v5
	v_fmamk_f32 v124, v92, 0x3e0293ee, v5
	v_fmamk_f32 v125, v93, 0x3e0293ee, v5
	v_fmamk_f32 v126, v94, 0x3e0293ee, v5
	v_fmac_f32_e32 v5, 0x3e0293ee, v95
	v_exp_f32_e32 v127, v6
	v_exp_f32_e32 v131, v7
	v_exp_f32_e32 v132, v8
	v_exp_f32_e32 v133, v9
	v_exp_f32_e32 v10, v10
	v_exp_f32_e32 v11, v11
	v_exp_f32_e32 v12, v12
	v_exp_f32_e32 v13, v13
	v_exp_f32_e32 v14, v14
	v_exp_f32_e32 v15, v15
	v_exp_f32_e32 v134, v96
	v_exp_f32_e32 v135, v97
	v_exp_f32_e32 v136, v98
	v_exp_f32_e32 v137, v99
	v_exp_f32_e32 v138, v100
	v_exp_f32_e32 v139, v101
	s_ashr_i32 s8, s68, 8
	v_lshl_add_u32 v6, s8, 2, v128
	ds_read_b128 v[96:99], v6
	ds_read_b128 v[100:103], v6 offset:32
	ds_read_b128 v[80:83], v6 offset:128
	ds_read_b128 v[84:87], v6 offset:160
	ds_read_b128 v[104:107], v6 offset:64
	ds_read_b128 v[108:111], v6 offset:96
	ds_read_b128 v[88:91], v6 offset:192
	ds_read_b128 v[92:95], v6 offset:224
	s_add_i32 s8, s68, 0
	v_add3_u32 v140, s8, v197, v196
	v_add3_u32 v141, s8, v198, v196
	v_add3_u32 v142, s8, v199, v196
	v_add3_u32 v143, s8, v200, v196
	s_setprio 1
	ds_read_b128 v[6:9], v140 offset:49152
	ds_read_b128 v[220:223], v140 offset:57344
	ds_read_b128 v[224:227], v141 offset:49152
	ds_read_b128 v[228:231], v141 offset:57344
	ds_read_b128 v[232:235], v142 offset:49152
	s_waitcnt lgkmcnt(4)
	v_mfma_f32_32x32x16_bf16 v[96:111], v[6:9], v[172:175], v[96:111]
	ds_read_b128 v[6:9], v142 offset:57344
	s_waitcnt lgkmcnt(4)
	v_mfma_f32_32x32x16_bf16 v[80:95], v[220:223], v[172:175], v[80:95]
	ds_read_b128 v[220:223], v143 offset:49152
	s_waitcnt lgkmcnt(4)
	v_mfma_f32_32x32x16_bf16 v[96:111], v[224:227], v[168:171], v[96:111]
	ds_read_b128 v[224:227], v143 offset:57344
	s_waitcnt lgkmcnt(4)
	v_mfma_f32_32x32x16_bf16 v[80:95], v[228:231], v[168:171], v[80:95]
	ds_read_b128 v[228:231], v140 offset:49280
	s_waitcnt lgkmcnt(4)
	v_mfma_f32_32x32x16_bf16 v[96:111], v[232:235], v[164:167], v[96:111]
	ds_read_b128 v[232:235], v140 offset:57472
	s_waitcnt lgkmcnt(4)
	v_mfma_f32_32x32x16_bf16 v[80:95], v[6:9], v[164:167], v[80:95]
	ds_read_b128 v[6:9], v141 offset:49280
	s_waitcnt lgkmcnt(4)
	v_mfma_f32_32x32x16_bf16 v[96:111], v[220:223], v[160:163], v[96:111]
	ds_read_b128 v[220:223], v141 offset:57472
	s_waitcnt lgkmcnt(4)
	v_mfma_f32_32x32x16_bf16 v[80:95], v[224:227], v[160:163], v[80:95]
	ds_read_b128 v[224:227], v142 offset:49280
	s_waitcnt lgkmcnt(4)
	v_mfma_f32_32x32x16_bf16 v[96:111], v[228:231], v[156:159], v[96:111]
	ds_read_b128 v[228:231], v142 offset:57472
	s_waitcnt lgkmcnt(4)
	v_mfma_f32_32x32x16_bf16 v[80:95], v[232:235], v[156:159], v[80:95]
	ds_read_b128 v[232:235], v143 offset:49280
	s_waitcnt lgkmcnt(4)
	v_mfma_f32_32x32x16_bf16 v[96:111], v[6:9], v[152:155], v[96:111]
	ds_read_b128 v[6:9], v143 offset:57472
	s_waitcnt lgkmcnt(4)
	v_mfma_f32_32x32x16_bf16 v[80:95], v[220:223], v[152:155], v[80:95]
	s_waitcnt lgkmcnt(3)
	v_mfma_f32_32x32x16_bf16 v[96:111], v[224:227], v[148:151], v[96:111]
	s_waitcnt lgkmcnt(2)
	v_mfma_f32_32x32x16_bf16 v[80:95], v[228:231], v[148:151], v[80:95]
	s_waitcnt lgkmcnt(1)
	v_mfma_f32_32x32x16_bf16 v[96:111], v[232:235], v[144:147], v[96:111]
	s_waitcnt lgkmcnt(0)
	v_mfma_f32_32x32x16_bf16 v[80:95], v[6:9], v[144:147], v[80:95]
	s_setprio 0
	v_exp_f32_e32 v7, v112
	v_exp_f32_e32 v112, v113
	v_exp_f32_e32 v113, v114
	v_exp_f32_e32 v114, v115
	v_exp_f32_e32 v115, v116
	v_exp_f32_e32 v116, v117
	v_exp_f32_e32 v117, v118
	v_exp_f32_e32 v118, v119
	v_exp_f32_e32 v119, v120
	v_exp_f32_e32 v120, v121
	v_exp_f32_e32 v121, v122
	v_exp_f32_e32 v122, v123
	v_exp_f32_e32 v123, v124
	v_exp_f32_e32 v124, v125
	v_exp_f32_e32 v125, v126
	v_exp_f32_e32 v126, v5
	v_add_f32_e32 v5, 0, v127
	v_add_f32_e32 v5, v131, v5
	v_add_f32_e32 v5, v132, v5
	v_add_f32_e32 v5, v133, v5
	v_add_f32_e32 v5, v10, v5
	v_add_f32_e32 v5, v11, v5
	v_add_f32_e32 v5, v12, v5
	v_add_f32_e32 v5, v13, v5
	v_add_f32_e32 v5, v14, v5
	v_add_f32_e32 v5, v15, v5
	v_add_f32_e32 v5, v134, v5
	v_add_f32_e32 v5, v135, v5
	v_add_f32_e32 v5, v136, v5
	v_add_f32_e32 v5, v137, v5
	v_add_f32_e32 v5, v138, v5
	v_add_f32_e32 v5, v139, v5
	v_add_f32_e32 v5, v7, v5
	v_add_f32_e32 v5, v112, v5
	v_add_f32_e32 v5, v113, v5
	v_add_f32_e32 v5, v114, v5
	v_add_f32_e32 v5, v115, v5
	v_add_f32_e32 v5, v116, v5
	v_add_f32_e32 v5, v117, v5
	v_add_f32_e32 v5, v118, v5
	v_add_f32_e32 v5, v119, v5
	v_add_f32_e32 v5, v120, v5
	v_add_f32_e32 v5, v121, v5
	v_add_f32_e32 v5, v122, v5
	v_add_f32_e32 v5, v123, v5
	v_add_f32_e32 v5, v124, v5
	v_add_f32_e32 v5, v125, v5
	v_add_f32_e32 v5, v126, v5
	v_mov_b32_e32 v6, v5
	s_nop 1
	v_permlane32_swap_b32_e32 v5, v6
	v_cvt_pk_bf16_f32 v8, v127, v131
	v_cvt_pk_bf16_f32 v9, v132, v133
	v_cvt_pk_bf16_f32 v10, v10, v11
	v_cvt_pk_bf16_f32 v11, v12, v13
	v_cvt_pk_bf16_f32 v12, v14, v15
	v_cvt_pk_bf16_f32 v13, v134, v135
	v_cvt_pk_bf16_f32 v14, v136, v137
	v_cvt_pk_bf16_f32 v15, v138, v139
	v_cvt_pk_bf16_f32 v112, v7, v112
	v_cvt_pk_bf16_f32 v113, v113, v114
	v_cvt_pk_bf16_f32 v114, v115, v116
	v_cvt_pk_bf16_f32 v115, v117, v118
	v_cvt_pk_bf16_f32 v116, v119, v120
	v_cvt_pk_bf16_f32 v117, v121, v122
	v_cvt_pk_bf16_f32 v118, v123, v124
	v_cvt_pk_bf16_f32 v119, v125, v126
	s_nop 0
	v_permlane32_swap_b32_e32 v8, v10
	v_permlane32_swap_b32_e32 v9, v11
	v_permlane32_swap_b32_e32 v12, v14
	v_permlane32_swap_b32_e32 v13, v15
	v_permlane32_swap_b32_e32 v112, v114
	v_permlane32_swap_b32_e32 v113, v115
	v_permlane32_swap_b32_e32 v116, v118
	v_permlane32_swap_b32_e32 v117, v119
	v_add_u32_e32 v7, s61, v193
	ds_read_b64_tr_b16 v[120:121], v7 offset:0
	ds_read_b64_tr_b16 v[122:123], v7 offset:0x800
	ds_read_b64_tr_b16 v[124:125], v7 offset:0x1000
	ds_read_b64_tr_b16 v[126:127], v7 offset:0x1800
	ds_read_b64_tr_b16 v[132:133], v7 offset:0x2000
	ds_read_b64_tr_b16 v[134:135], v7 offset:0x2800
	ds_read_b64_tr_b16 v[136:137], v7 offset:0x3000
	ds_read_b64_tr_b16 v[138:139], v7 offset:0x3800
	s_waitcnt lgkmcnt(6)
	s_nop 0
	v_mfma_f32_32x32x16_bf16 v[16:31], v[8:11], v[120:123], v[16:31]
	ds_read_b64_tr_b16 v[120:121], v7 offset:0x200
	ds_read_b64_tr_b16 v[122:123], v7 offset:0xa00
	s_waitcnt lgkmcnt(6)
	v_mfma_f32_32x32x16_bf16 v[16:31], v[12:15], v[124:127], v[16:31]
	ds_read_b64_tr_b16 v[124:125], v7 offset:0x1200
	ds_read_b64_tr_b16 v[126:127], v7 offset:0x1a00
	s_waitcnt lgkmcnt(6)
	v_mfma_f32_32x32x16_bf16 v[16:31], v[112:115], v[132:135], v[16:31]
	ds_read_b64_tr_b16 v[132:133], v7 offset:0x2200
	ds_read_b64_tr_b16 v[134:135], v7 offset:0x2a00
	s_waitcnt lgkmcnt(6)
	v_mfma_f32_32x32x16_bf16 v[16:31], v[116:119], v[136:139], v[16:31]
	ds_read_b64_tr_b16 v[136:137], v7 offset:0x3200
	ds_read_b64_tr_b16 v[138:139], v7 offset:0x3a00
	s_waitcnt lgkmcnt(6)
	v_mfma_f32_32x32x16_bf16 v[48:63], v[8:11], v[120:123], v[48:63]
	ds_read_b64_tr_b16 v[120:121], v7 offset:0x400
	ds_read_b64_tr_b16 v[122:123], v7 offset:0xc00
	s_waitcnt lgkmcnt(6)
	v_mfma_f32_32x32x16_bf16 v[48:63], v[12:15], v[124:127], v[48:63]
	ds_read_b64_tr_b16 v[124:125], v7 offset:0x1400
	ds_read_b64_tr_b16 v[126:127], v7 offset:0x1c00
	s_waitcnt lgkmcnt(6)
	v_mfma_f32_32x32x16_bf16 v[48:63], v[112:115], v[132:135], v[48:63]
	ds_read_b64_tr_b16 v[132:133], v7 offset:0x2400
	ds_read_b64_tr_b16 v[134:135], v7 offset:0x2c00
	s_waitcnt lgkmcnt(6)
	v_mfma_f32_32x32x16_bf16 v[48:63], v[116:119], v[136:139], v[48:63]
	ds_read_b64_tr_b16 v[136:137], v7 offset:0x3400
	ds_read_b64_tr_b16 v[138:139], v7 offset:0x3c00
	s_waitcnt lgkmcnt(6)
	v_mfma_f32_32x32x16_bf16 v[64:79], v[8:11], v[120:123], v[64:79]
	ds_read_b64_tr_b16 v[120:121], v7 offset:0x600
	ds_read_b64_tr_b16 v[122:123], v7 offset:0xe00
	s_waitcnt lgkmcnt(6)
	v_mfma_f32_32x32x16_bf16 v[64:79], v[12:15], v[124:127], v[64:79]
	ds_read_b64_tr_b16 v[124:125], v7 offset:0x1600
	ds_read_b64_tr_b16 v[126:127], v7 offset:0x1e00
	s_waitcnt lgkmcnt(6)
	v_mfma_f32_32x32x16_bf16 v[64:79], v[112:115], v[132:135], v[64:79]
	ds_read_b64_tr_b16 v[132:133], v7 offset:0x2600
	ds_read_b64_tr_b16 v[134:135], v7 offset:0x2e00
	s_waitcnt lgkmcnt(6)
	v_mfma_f32_32x32x16_bf16 v[64:79], v[116:119], v[136:139], v[64:79]
	ds_read_b64_tr_b16 v[136:137], v7 offset:0x3600
	ds_read_b64_tr_b16 v[138:139], v7 offset:0x3e00
	s_waitcnt lgkmcnt(6)
	v_mfma_f32_32x32x16_bf16 v[32:47], v[8:11], v[120:123], v[32:47]
	s_cmp_le_i32 s91, s69
	s_waitcnt lgkmcnt(4)
	v_mfma_f32_32x32x16_bf16 v[32:47], v[12:15], v[124:127], v[32:47]
	s_waitcnt lgkmcnt(2)
	v_mfma_f32_32x32x16_bf16 v[32:47], v[112:115], v[132:135], v[32:47]
	s_waitcnt lgkmcnt(0)
	v_mfma_f32_32x32x16_bf16 v[32:47], v[116:119], v[136:139], v[32:47]
	s_cbranch_scc1 .LBB0_1177
	v_add_u32_e32 v7, 0x4000007b, v130
	v_cmp_gt_u32_e32 vcc, 2.0, v7
	v_add_u32_e32 v7, 0x5b, v130
	s_nop 0
	v_cndmask_b32_e32 v96, v179, v96, vcc
	v_cmp_lt_u32_e32 vcc, s96, v7
	v_add_u32_e32 v7, 0x7a, v130
	s_nop 0
	v_cndmask_b32_e32 v80, v179, v80, vcc
	v_cmp_lt_u32_e32 vcc, s96, v7
	v_add_u32_e32 v7, 0x5a, v130
	s_nop 0
	v_cndmask_b32_e32 v97, v179, v97, vcc
	v_cmp_lt_u32_e32 vcc, s96, v7
	v_add_u32_e32 v7, 0x79, v130
	s_nop 0
	v_cndmask_b32_e32 v81, v179, v81, vcc
	v_cmp_lt_u32_e32 vcc, s96, v7
	v_add_u32_e32 v7, 0x59, v130
	s_nop 0
	v_cndmask_b32_e32 v98, v179, v98, vcc
	v_cmp_lt_u32_e32 vcc, s96, v7
	v_add_u32_e32 v7, 0x78, v130
	s_nop 0
	v_cndmask_b32_e32 v82, v179, v82, vcc
	v_cmp_lt_u32_e32 vcc, s96, v7
	v_add_u32_e32 v7, 0x58, v130
	s_nop 0
	v_cndmask_b32_e32 v99, v179, v99, vcc
	v_cmp_lt_u32_e32 vcc, s96, v7
	v_add_u32_e32 v7, 0x73, v130
	s_nop 0
	v_cndmask_b32_e32 v83, v179, v83, vcc
	v_cmp_lt_u32_e32 vcc, s96, v7
	v_add_u32_e32 v7, 0x53, v130
	s_nop 0
	v_cndmask_b32_e32 v100, v179, v100, vcc
	v_cmp_lt_u32_e32 vcc, s96, v7
	v_add_u32_e32 v7, 0x72, v130
	s_nop 0
	v_cndmask_b32_e32 v84, v179, v84, vcc
	v_cmp_lt_u32_e32 vcc, s96, v7
	v_add_u32_e32 v7, 0x52, v130
	s_nop 0
	v_cndmask_b32_e32 v101, v179, v101, vcc
	v_cmp_lt_u32_e32 vcc, s96, v7
	v_add_u32_e32 v7, 0x71, v130
	s_nop 0
	v_cndmask_b32_e32 v85, v179, v85, vcc
	v_cmp_lt_u32_e32 vcc, s96, v7
	v_add_u32_e32 v7, 0x51, v130
	s_nop 0
	v_cndmask_b32_e32 v102, v179, v102, vcc
	v_cmp_lt_u32_e32 vcc, s96, v7
	v_add_u32_e32 v7, 0x70, v130
	s_nop 0
	v_cndmask_b32_e32 v86, v179, v86, vcc
	v_cmp_lt_u32_e32 vcc, s96, v7
	v_add_u32_e32 v7, 0x50, v130
	s_nop 0
	v_cndmask_b32_e32 v103, v179, v103, vcc
	v_cmp_lt_u32_e32 vcc, s96, v7
	v_add_u32_e32 v7, 0x6b, v130
	s_nop 0
	v_cndmask_b32_e32 v87, v179, v87, vcc
	v_cmp_lt_u32_e32 vcc, s96, v7
	v_add_u32_e32 v7, 0x4b, v130
	s_nop 0
	v_cndmask_b32_e32 v104, v179, v104, vcc
	v_cmp_lt_u32_e32 vcc, s96, v7
	v_add_u32_e32 v7, 0x6a, v130
	s_nop 0
	v_cndmask_b32_e32 v88, v179, v88, vcc
	v_cmp_lt_u32_e32 vcc, s96, v7
	v_add_u32_e32 v7, 0x4a, v130
	s_nop 0
	v_cndmask_b32_e32 v105, v179, v105, vcc
	v_cmp_lt_u32_e32 vcc, s96, v7
	v_add_u32_e32 v7, 0x69, v130
	s_nop 0
	v_cndmask_b32_e32 v89, v179, v89, vcc
	v_cmp_lt_u32_e32 vcc, s96, v7
	v_add_u32_e32 v7, 0x49, v130
	s_nop 0
	v_cndmask_b32_e32 v106, v179, v106, vcc
	v_cmp_lt_u32_e32 vcc, s96, v7
	v_add_u32_e32 v7, 0x68, v130
	s_nop 0
	v_cndmask_b32_e32 v90, v179, v90, vcc
	v_cmp_lt_u32_e32 vcc, s96, v7
	v_add_u32_e32 v7, 0x48, v130
	s_nop 0
	v_cndmask_b32_e32 v107, v179, v107, vcc
	v_cmp_lt_u32_e32 vcc, s96, v7
	v_add_u32_e32 v7, 0x63, v130
	s_nop 0
	v_cndmask_b32_e32 v91, v179, v91, vcc
	v_cmp_lt_u32_e32 vcc, s96, v7
	v_add_u32_e32 v7, 0x43, v130
	s_nop 0
	v_cndmask_b32_e32 v108, v179, v108, vcc
	v_cmp_lt_u32_e32 vcc, s96, v7
	v_add_u32_e32 v7, 0x62, v130
	s_nop 0
	v_cndmask_b32_e32 v92, v179, v92, vcc
	v_cmp_lt_u32_e32 vcc, s96, v7
	v_add_u32_e32 v7, 0x42, v130
	s_nop 0
	v_cndmask_b32_e32 v109, v179, v109, vcc
	v_cmp_lt_u32_e32 vcc, s96, v7
	v_add_u32_e32 v7, 0x61, v130
	s_nop 0
	v_cndmask_b32_e32 v93, v179, v93, vcc
	v_cmp_lt_u32_e32 vcc, s96, v7
	v_add_u32_e32 v7, 0x41, v130
	s_nop 0
	v_cndmask_b32_e32 v110, v179, v110, vcc
	v_cmp_lt_u32_e32 vcc, s96, v7
	v_add_u32_e32 v7, 0x60, v130
	s_nop 0
	v_cndmask_b32_e32 v94, v179, v94, vcc
	v_cmp_lt_u32_e32 vcc, s96, v7
	v_add_u32_e32 v7, 64, v130
	s_nop 0
	v_cndmask_b32_e32 v111, v179, v111, vcc
	v_cmp_lt_u32_e32 vcc, s96, v7
	s_nop 1
	v_cndmask_b32_e32 v95, v179, v95, vcc

.LBB0_1189:
	s_add_i32 s8, s0, 2
	s_ashr_i32 s9, s8, 31
	s_lshl_b64 s[8:9], s[8:9], 14
	s_add_u32 s8, s56, s8
	s_addc_u32 s9, s57, s9
	s_add_i32 s1, s68, s83
	s_mov_b32 s64, m0
	s_mov_b32 m0, s1
	s_nop 0
	global_load_lds_dwordx4 v187, s[8:9]
	s_mov_b32 m0, s64
	s_addk_i32 s1, 0x400
	s_mov_b32 s64, m0
	s_mov_b32 m0, s1
	s_nop 0
	global_load_lds_dwordx4 v186, s[8:9]
	s_mov_b32 m0, s64
	s_ashr_i32 s1, s66, 8
	v_lshl_add_u32 v2, s1, 2, v128
	ds_read_b128 v[96:99], v2
	ds_read_b128 v[100:103], v2 offset:32
	ds_read_b128 v[80:83], v2 offset:128
	ds_read_b128 v[84:87], v2 offset:160
	ds_read_b128 v[104:107], v2 offset:64
	ds_read_b128 v[108:111], v2 offset:96
	ds_read_b128 v[88:91], v2 offset:192
	ds_read_b128 v[92:95], v2 offset:224
	s_add_i32 s1, s66, 0
	v_add3_u32 v6, s1, v197, v196
	v_add3_u32 v7, s1, v198, v196
	v_add3_u32 v8, s1, v199, v196
	v_add3_u32 v9, s1, v200, v196
	s_setprio 1
	ds_read_b128 v[2:5], v6 offset:49152
	ds_read_b128 v[220:223], v6 offset:57344
	ds_read_b128 v[224:227], v7 offset:49152
	ds_read_b128 v[228:231], v7 offset:57344
	ds_read_b128 v[232:235], v8 offset:49152
	s_waitcnt lgkmcnt(4)
	v_mfma_f32_32x32x16_bf16 v[96:111], v[2:5], v[172:175], v[96:111]
	ds_read_b128 v[2:5], v8 offset:57344
	s_waitcnt lgkmcnt(4)
	v_mfma_f32_32x32x16_bf16 v[80:95], v[220:223], v[172:175], v[80:95]
	ds_read_b128 v[220:223], v9 offset:49152
	s_waitcnt lgkmcnt(4)
	v_mfma_f32_32x32x16_bf16 v[96:111], v[224:227], v[168:171], v[96:111]
	ds_read_b128 v[224:227], v9 offset:57344
	s_waitcnt lgkmcnt(4)
	v_mfma_f32_32x32x16_bf16 v[80:95], v[228:231], v[168:171], v[80:95]
	ds_read_b128 v[228:231], v6 offset:49280
	s_waitcnt lgkmcnt(4)
	v_mfma_f32_32x32x16_bf16 v[96:111], v[232:235], v[164:167], v[96:111]
	ds_read_b128 v[232:235], v6 offset:57472
	s_waitcnt lgkmcnt(4)
	v_mfma_f32_32x32x16_bf16 v[80:95], v[2:5], v[164:167], v[80:95]
	ds_read_b128 v[2:5], v7 offset:49280
	s_waitcnt lgkmcnt(4)
	v_mfma_f32_32x32x16_bf16 v[96:111], v[220:223], v[160:163], v[96:111]
	ds_read_b128 v[220:223], v7 offset:57472
	s_waitcnt lgkmcnt(4)
	v_mfma_f32_32x32x16_bf16 v[80:95], v[224:227], v[160:163], v[80:95]
	ds_read_b128 v[224:227], v8 offset:49280
	s_waitcnt lgkmcnt(4)
	v_mfma_f32_32x32x16_bf16 v[96:111], v[228:231], v[156:159], v[96:111]
	ds_read_b128 v[228:231], v8 offset:57472
	s_waitcnt lgkmcnt(4)
	v_mfma_f32_32x32x16_bf16 v[80:95], v[232:235], v[156:159], v[80:95]
	ds_read_b128 v[232:235], v9 offset:49280
	s_waitcnt lgkmcnt(4)
	v_mfma_f32_32x32x16_bf16 v[96:111], v[2:5], v[152:155], v[96:111]
	ds_read_b128 v[2:5], v9 offset:57472
	s_waitcnt lgkmcnt(4)
	v_mfma_f32_32x32x16_bf16 v[80:95], v[220:223], v[152:155], v[80:95]
	s_waitcnt lgkmcnt(3)
	v_mfma_f32_32x32x16_bf16 v[96:111], v[224:227], v[148:151], v[96:111]
	s_waitcnt lgkmcnt(2)
	v_mfma_f32_32x32x16_bf16 v[80:95], v[228:231], v[148:151], v[80:95]
	s_waitcnt lgkmcnt(1)
	v_mfma_f32_32x32x16_bf16 v[96:111], v[232:235], v[144:147], v[96:111]
	s_waitcnt lgkmcnt(0)
	v_mfma_f32_32x32x16_bf16 v[80:95], v[2:5], v[144:147], v[80:95]
	s_setprio 0
	v_add_f32_e32 v3, 0, v215
	v_add_f32_e32 v3, v217, v3
	v_add_f32_e32 v3, v213, v3
	v_add_f32_e32 v3, v216, v3
	v_add_f32_e32 v3, v211, v3
	v_add_f32_e32 v3, v214, v3
	v_add_f32_e32 v3, v210, v3
	v_add_f32_e32 v3, v212, v3
	v_add_f32_e32 v3, v205, v3
	v_add_f32_e32 v3, v208, v3
	v_add_f32_e32 v3, v203, v3
	v_add_f32_e32 v3, v206, v3
	v_exp_f32_e32 v2, v126
	v_add_f32_e32 v3, v202, v3
	v_exp_f32_e32 v5, v127
	v_add_f32_e32 v3, v209, v3
	v_exp_f32_e32 v14, v124
	v_add_f32_e32 v3, v204, v3
	v_exp_f32_e32 v15, v125
	v_add_f32_e32 v3, v207, v3
	v_exp_f32_e32 v122, v122
	v_add_f32_e32 v3, v2, v3
	v_exp_f32_e32 v123, v123
	v_add_f32_e32 v3, v5, v3
	v_exp_f32_e32 v120, v120
	v_add_f32_e32 v3, v14, v3
	v_exp_f32_e32 v121, v121
	v_add_f32_e32 v3, v15, v3
	v_exp_f32_e32 v118, v118
	v_add_f32_e32 v3, v122, v3
	v_exp_f32_e32 v119, v119
	v_add_f32_e32 v3, v123, v3
	v_exp_f32_e32 v124, v116
	v_add_f32_e32 v3, v120, v3
	v_exp_f32_e32 v117, v117
	v_add_f32_e32 v3, v121, v3
	v_exp_f32_e32 v125, v114
	v_add_f32_e32 v3, v118, v3
	v_exp_f32_e32 v126, v115
	v_add_f32_e32 v3, v119, v3
	v_exp_f32_e32 v127, v112
	v_add_f32_e32 v3, v124, v3
	v_exp_f32_e32 v130, v113
	v_add_f32_e32 v3, v117, v3
	v_add_f32_e32 v3, v125, v3
	v_add_f32_e32 v3, v126, v3
	v_add_f32_e32 v3, v127, v3
	v_add_f32_e32 v3, v130, v3
	v_mov_b32_e32 v4, v3
	s_nop 1
	v_permlane32_swap_b32_e32 v3, v4
	v_cvt_pk_bf16_f32 v6, v215, v217
	v_cvt_pk_bf16_f32 v7, v213, v216
	v_cvt_pk_bf16_f32 v8, v211, v214
	v_cvt_pk_bf16_f32 v9, v210, v212
	v_cvt_pk_bf16_f32 v10, v205, v208
	v_cvt_pk_bf16_f32 v11, v203, v206
	v_cvt_pk_bf16_f32 v12, v202, v209
	v_cvt_pk_bf16_f32 v13, v204, v207
	v_cvt_pk_bf16_f32 v112, v2, v5
	v_cvt_pk_bf16_f32 v113, v14, v15
	v_cvt_pk_bf16_f32 v114, v122, v123
	v_cvt_pk_bf16_f32 v115, v120, v121
	v_cvt_pk_bf16_f32 v116, v118, v119
	v_cvt_pk_bf16_f32 v117, v124, v117
	v_cvt_pk_bf16_f32 v118, v125, v126
	v_cvt_pk_bf16_f32 v119, v127, v130
	s_nop 0
	v_permlane32_swap_b32_e32 v6, v8
	v_permlane32_swap_b32_e32 v7, v9
	v_permlane32_swap_b32_e32 v10, v12
	v_permlane32_swap_b32_e32 v11, v13
	v_permlane32_swap_b32_e32 v112, v114
	v_permlane32_swap_b32_e32 v113, v115
	v_permlane32_swap_b32_e32 v116, v118
	v_permlane32_swap_b32_e32 v117, v119
	v_add_u32_e32 v2, s53, v193
	ds_read_b64_tr_b16 v[120:121], v2 offset:0
	ds_read_b64_tr_b16 v[122:123], v2 offset:0x800
	ds_read_b64_tr_b16 v[124:125], v2 offset:0x1000
	ds_read_b64_tr_b16 v[126:127], v2 offset:0x1800
	ds_read_b64_tr_b16 v[130:131], v2 offset:0x2000
	ds_read_b64_tr_b16 v[132:133], v2 offset:0x2800
	ds_read_b64_tr_b16 v[134:135], v2 offset:0x3000
	ds_read_b64_tr_b16 v[136:137], v2 offset:0x3800
	s_waitcnt lgkmcnt(6)
	s_nop 0
	v_mfma_f32_32x32x16_bf16 v[16:31], v[6:9], v[120:123], v[16:31]
	ds_read_b64_tr_b16 v[120:121], v2 offset:0x200
	ds_read_b64_tr_b16 v[122:123], v2 offset:0xa00
	s_waitcnt lgkmcnt(6)
	v_mfma_f32_32x32x16_bf16 v[16:31], v[10:13], v[124:127], v[16:31]
	ds_read_b64_tr_b16 v[124:125], v2 offset:0x1200
	ds_read_b64_tr_b16 v[126:127], v2 offset:0x1a00
	s_waitcnt lgkmcnt(6)
	v_mfma_f32_32x32x16_bf16 v[16:31], v[112:115], v[130:133], v[16:31]
	ds_read_b64_tr_b16 v[130:131], v2 offset:0x2200
	ds_read_b64_tr_b16 v[132:133], v2 offset:0x2a00
	s_waitcnt lgkmcnt(6)
	v_mfma_f32_32x32x16_bf16 v[16:31], v[116:119], v[134:137], v[16:31]
	ds_read_b64_tr_b16 v[134:135], v2 offset:0x3200
	ds_read_b64_tr_b16 v[136:137], v2 offset:0x3a00
	s_waitcnt lgkmcnt(6)
	v_mfma_f32_32x32x16_bf16 v[48:63], v[6:9], v[120:123], v[48:63]
	ds_read_b64_tr_b16 v[120:121], v2 offset:0x400
	ds_read_b64_tr_b16 v[122:123], v2 offset:0xc00
	s_waitcnt lgkmcnt(6)
	v_mfma_f32_32x32x16_bf16 v[48:63], v[10:13], v[124:127], v[48:63]
	ds_read_b64_tr_b16 v[124:125], v2 offset:0x1400
	ds_read_b64_tr_b16 v[126:127], v2 offset:0x1c00
	s_waitcnt lgkmcnt(6)
	v_mfma_f32_32x32x16_bf16 v[48:63], v[112:115], v[130:133], v[48:63]
	ds_read_b64_tr_b16 v[130:131], v2 offset:0x2400
	ds_read_b64_tr_b16 v[132:133], v2 offset:0x2c00
	s_waitcnt lgkmcnt(6)
	v_mfma_f32_32x32x16_bf16 v[48:63], v[116:119], v[134:137], v[48:63]
	ds_read_b64_tr_b16 v[134:135], v2 offset:0x3400
	ds_read_b64_tr_b16 v[136:137], v2 offset:0x3c00
	s_waitcnt lgkmcnt(6)
	v_mfma_f32_32x32x16_bf16 v[64:79], v[6:9], v[120:123], v[64:79]
	ds_read_b64_tr_b16 v[120:121], v2 offset:0x600
	ds_read_b64_tr_b16 v[122:123], v2 offset:0xe00
	s_waitcnt lgkmcnt(6)
	v_mfma_f32_32x32x16_bf16 v[64:79], v[10:13], v[124:127], v[64:79]
	ds_read_b64_tr_b16 v[124:125], v2 offset:0x1600
	ds_read_b64_tr_b16 v[126:127], v2 offset:0x1e00
	s_waitcnt lgkmcnt(6)
	v_mfma_f32_32x32x16_bf16 v[64:79], v[112:115], v[130:133], v[64:79]
	ds_read_b64_tr_b16 v[130:131], v2 offset:0x2600
	ds_read_b64_tr_b16 v[132:133], v2 offset:0x2e00
	s_waitcnt lgkmcnt(6)
	v_mfma_f32_32x32x16_bf16 v[64:79], v[116:119], v[134:137], v[64:79]
	ds_read_b64_tr_b16 v[134:135], v2 offset:0x3600
	ds_read_b64_tr_b16 v[136:137], v2 offset:0x3e00
	s_waitcnt lgkmcnt(6)
	v_mfma_f32_32x32x16_bf16 v[32:47], v[6:9], v[120:123], v[32:47]
	s_add_i32 s1, s70, 64
	s_cmp_le_i32 s1, s69
	s_waitcnt lgkmcnt(4)
	v_mfma_f32_32x32x16_bf16 v[32:47], v[10:13], v[124:127], v[32:47]
	s_waitcnt lgkmcnt(2)
	v_mfma_f32_32x32x16_bf16 v[32:47], v[112:115], v[130:133], v[32:47]
	s_waitcnt lgkmcnt(0)
	v_mfma_f32_32x32x16_bf16 v[32:47], v[116:119], v[134:137], v[32:47]
	s_cbranch_scc1 .LBB0_1191
	v_add_u32_e32 v2, 0x4000003b, v1
	v_cmp_gt_u32_e32 vcc, 2.0, v2
	v_add_u32_e32 v2, 27, v1
	s_nop 0
	v_cndmask_b32_e32 v96, v179, v96, vcc
	v_cmp_lt_u32_e32 vcc, s96, v2
	v_add_u32_e32 v2, 58, v1
	s_nop 0
	v_cndmask_b32_e32 v80, v179, v80, vcc
	v_cmp_lt_u32_e32 vcc, s96, v2
	v_add_u32_e32 v2, 26, v1
	s_nop 0
	v_cndmask_b32_e32 v97, v179, v97, vcc
	v_cmp_lt_u32_e32 vcc, s96, v2
	v_add_u32_e32 v2, 57, v1
	s_nop 0
	v_cndmask_b32_e32 v81, v179, v81, vcc
	v_cmp_lt_u32_e32 vcc, s96, v2
	v_add_u32_e32 v2, 25, v1
	s_nop 0
	v_cndmask_b32_e32 v98, v179, v98, vcc
	v_cmp_lt_u32_e32 vcc, s96, v2
	v_add_u32_e32 v2, 56, v1
	s_nop 0
	v_cndmask_b32_e32 v82, v179, v82, vcc
	v_cmp_lt_u32_e32 vcc, s96, v2
	v_add_u32_e32 v2, 24, v1
	s_nop 0
	v_cndmask_b32_e32 v99, v179, v99, vcc
	v_cmp_lt_u32_e32 vcc, s96, v2
	v_add_u32_e32 v2, 51, v1
	s_nop 0
	v_cndmask_b32_e32 v83, v179, v83, vcc
	v_cmp_lt_u32_e32 vcc, s96, v2
	v_add_u32_e32 v2, 19, v1
	s_nop 0
	v_cndmask_b32_e32 v100, v179, v100, vcc
	v_cmp_lt_u32_e32 vcc, s96, v2
	v_add_u32_e32 v2, 50, v1
	s_nop 0
	v_cndmask_b32_e32 v84, v179, v84, vcc
	v_cmp_lt_u32_e32 vcc, s96, v2
	v_add_u32_e32 v2, 18, v1
	s_nop 0
	v_cndmask_b32_e32 v101, v179, v101, vcc
	v_cmp_lt_u32_e32 vcc, s96, v2
	v_add_u32_e32 v2, 49, v1
	s_nop 0
	v_cndmask_b32_e32 v85, v179, v85, vcc
	v_cmp_lt_u32_e32 vcc, s96, v2
	v_add_u32_e32 v2, 17, v1
	s_nop 0
	v_cndmask_b32_e32 v102, v179, v102, vcc
	v_cmp_lt_u32_e32 vcc, s96, v2
	v_add_u32_e32 v2, 48, v1
	s_nop 0
	v_cndmask_b32_e32 v86, v179, v86, vcc
	v_cmp_lt_u32_e32 vcc, s96, v2
	v_add_u32_e32 v2, 16, v1
	s_nop 0
	v_cndmask_b32_e32 v103, v179, v103, vcc
	v_cmp_lt_u32_e32 vcc, s96, v2
	v_add_u32_e32 v2, 43, v1
	s_nop 0
	v_cndmask_b32_e32 v87, v179, v87, vcc
	v_cmp_lt_u32_e32 vcc, s96, v2
	v_add_u32_e32 v2, 11, v1
	s_nop 0
	v_cndmask_b32_e32 v104, v179, v104, vcc
	v_cmp_lt_u32_e32 vcc, s96, v2
	v_add_u32_e32 v2, 42, v1
	s_nop 0
	v_cndmask_b32_e32 v88, v179, v88, vcc
	v_cmp_lt_u32_e32 vcc, s96, v2
	v_add_u32_e32 v2, 10, v1
	s_nop 0
	v_cndmask_b32_e32 v105, v179, v105, vcc
	v_cmp_lt_u32_e32 vcc, s96, v2
	v_add_u32_e32 v2, 41, v1
	s_nop 0
	v_cndmask_b32_e32 v89, v179, v89, vcc
	v_cmp_lt_u32_e32 vcc, s96, v2
	v_add_u32_e32 v2, 9, v1
	s_nop 0
	v_cndmask_b32_e32 v106, v179, v106, vcc
	v_cmp_lt_u32_e32 vcc, s96, v2
	v_add_u32_e32 v2, 40, v1
	s_nop 0
	v_cndmask_b32_e32 v90, v179, v90, vcc
	v_cmp_lt_u32_e32 vcc, s96, v2
	v_add_u32_e32 v2, 8, v1
	s_nop 0
	v_cndmask_b32_e32 v107, v179, v107, vcc
	v_cmp_lt_u32_e32 vcc, s96, v2
	v_add_u32_e32 v2, 35, v1
	s_nop 0
	v_cndmask_b32_e32 v91, v179, v91, vcc
	v_cmp_lt_u32_e32 vcc, s96, v2
	v_add_u32_e32 v2, 3, v1
	s_nop 0
	v_cndmask_b32_e32 v108, v179, v108, vcc
	v_cmp_lt_u32_e32 vcc, s96, v2
	v_add_u32_e32 v2, 34, v1
	s_nop 0
	v_cndmask_b32_e32 v92, v179, v92, vcc
	v_cmp_lt_u32_e32 vcc, s96, v2
	v_add_u32_e32 v2, 2, v1
	s_nop 0
	v_cndmask_b32_e32 v109, v179, v109, vcc
	v_cmp_lt_u32_e32 vcc, s96, v2
	v_add_u32_e32 v2, 33, v1
	s_nop 0
	v_cndmask_b32_e32 v93, v179, v93, vcc
	v_cmp_lt_u32_e32 vcc, s96, v2
	v_add_u32_e32 v2, 1, v1
	s_nop 0
	v_cndmask_b32_e32 v110, v179, v110, vcc
	v_cmp_lt_u32_e32 vcc, s96, v2
	v_add_u32_e32 v2, 32, v1
	s_nop 0
	v_cndmask_b32_e32 v94, v179, v94, vcc
	v_cmp_lt_u32_e32 vcc, s96, v2
	s_nop 1
	v_cndmask_b32_e32 v111, v179, v111, vcc
	v_cmp_lt_u32_e32 vcc, s96, v1
	s_nop 1
	v_cndmask_b32_e32 v95, v179, v95, vcc

.LBB0_1200:
	v_cndmask_b32_e64 v2, v2, v201, s[8:9]
	v_mul_f32_e32 v5, 0xbe0293ee, v2
	v_fmamk_f32 v7, v96, 0x3e0293ee, v5
	v_fmamk_f32 v8, v97, 0x3e0293ee, v5
	v_fmamk_f32 v9, v98, 0x3e0293ee, v5
	v_fmamk_f32 v10, v99, 0x3e0293ee, v5
	v_fmamk_f32 v11, v100, 0x3e0293ee, v5
	v_fmamk_f32 v12, v101, 0x3e0293ee, v5
	v_fmamk_f32 v13, v102, 0x3e0293ee, v5
	v_fmamk_f32 v14, v103, 0x3e0293ee, v5
	v_fmamk_f32 v15, v104, 0x3e0293ee, v5
	v_fmamk_f32 v96, v105, 0x3e0293ee, v5
	v_fmamk_f32 v97, v106, 0x3e0293ee, v5
	v_fmamk_f32 v98, v107, 0x3e0293ee, v5
	v_fmamk_f32 v99, v108, 0x3e0293ee, v5
	v_fmamk_f32 v100, v109, 0x3e0293ee, v5
	v_fmamk_f32 v101, v110, 0x3e0293ee, v5
	v_fmamk_f32 v102, v111, 0x3e0293ee, v5
	v_exp_f32_e32 v125, v7
	v_fmamk_f32 v7, v93, 0x3e0293ee, v5
	v_fmamk_f32 v112, v80, 0x3e0293ee, v5
	v_fmamk_f32 v113, v81, 0x3e0293ee, v5
	v_fmamk_f32 v114, v82, 0x3e0293ee, v5
	v_fmamk_f32 v115, v83, 0x3e0293ee, v5
	v_fmamk_f32 v116, v84, 0x3e0293ee, v5
	v_fmamk_f32 v117, v85, 0x3e0293ee, v5
	v_fmamk_f32 v118, v86, 0x3e0293ee, v5
	v_fmamk_f32 v119, v87, 0x3e0293ee, v5
	v_fmamk_f32 v120, v88, 0x3e0293ee, v5
	v_fmamk_f32 v121, v89, 0x3e0293ee, v5
	v_fmamk_f32 v122, v90, 0x3e0293ee, v5
	v_fmamk_f32 v123, v91, 0x3e0293ee, v5
	v_fmamk_f32 v124, v92, 0x3e0293ee, v5
	v_exp_f32_e32 v126, v8
	v_exp_f32_e32 v127, v9
	v_exp_f32_e32 v130, v10
	v_exp_f32_e32 v131, v11
	v_exp_f32_e32 v12, v12
	v_exp_f32_e32 v13, v13
	v_exp_f32_e32 v14, v14
	v_exp_f32_e32 v15, v15
	v_exp_f32_e32 v132, v96
	v_exp_f32_e32 v133, v97
	v_exp_f32_e32 v134, v98
	v_exp_f32_e32 v135, v99
	v_exp_f32_e32 v136, v100
	v_exp_f32_e32 v137, v101
	v_exp_f32_e32 v138, v102
	v_fmamk_f32 v139, v94, 0x3e0293ee, v5
	v_fmac_f32_e32 v5, 0x3e0293ee, v95
	s_ashr_i32 s1, s68, 8
	v_lshl_add_u32 v8, s1, 2, v128
	ds_read_b128 v[96:99], v8
	ds_read_b128 v[100:103], v8 offset:32
	ds_read_b128 v[80:83], v8 offset:128
	ds_read_b128 v[84:87], v8 offset:160
	ds_read_b128 v[104:107], v8 offset:64
	ds_read_b128 v[108:111], v8 offset:96
	ds_read_b128 v[88:91], v8 offset:192
	ds_read_b128 v[92:95], v8 offset:224
	s_add_i32 s1, s68, 0
	v_add3_u32 v140, s1, v197, v196
	v_add3_u32 v141, s1, v198, v196
	v_add3_u32 v142, s1, v199, v196
	v_add3_u32 v143, s1, v200, v196
	s_setprio 1
	ds_read_b128 v[8:11], v140 offset:49152
	ds_read_b128 v[220:223], v140 offset:57344
	ds_read_b128 v[224:227], v141 offset:49152
	ds_read_b128 v[228:231], v141 offset:57344
	ds_read_b128 v[232:235], v142 offset:49152
	s_waitcnt lgkmcnt(4)
	v_mfma_f32_32x32x16_bf16 v[96:111], v[8:11], v[172:175], v[96:111]
	ds_read_b128 v[8:11], v142 offset:57344
	s_waitcnt lgkmcnt(4)
	v_mfma_f32_32x32x16_bf16 v[80:95], v[220:223], v[172:175], v[80:95]
	ds_read_b128 v[220:223], v143 offset:49152
	s_waitcnt lgkmcnt(4)
	v_mfma_f32_32x32x16_bf16 v[96:111], v[224:227], v[168:171], v[96:111]
	ds_read_b128 v[224:227], v143 offset:57344
	s_waitcnt lgkmcnt(4)
	v_mfma_f32_32x32x16_bf16 v[80:95], v[228:231], v[168:171], v[80:95]
	ds_read_b128 v[228:231], v140 offset:49280
	s_waitcnt lgkmcnt(4)
	v_mfma_f32_32x32x16_bf16 v[96:111], v[232:235], v[164:167], v[96:111]
	ds_read_b128 v[232:235], v140 offset:57472
	s_waitcnt lgkmcnt(4)
	v_mfma_f32_32x32x16_bf16 v[80:95], v[8:11], v[164:167], v[80:95]
	ds_read_b128 v[8:11], v141 offset:49280
	s_waitcnt lgkmcnt(4)
	v_mfma_f32_32x32x16_bf16 v[96:111], v[220:223], v[160:163], v[96:111]
	ds_read_b128 v[220:223], v141 offset:57472
	s_waitcnt lgkmcnt(4)
	v_mfma_f32_32x32x16_bf16 v[80:95], v[224:227], v[160:163], v[80:95]
	ds_read_b128 v[224:227], v142 offset:49280
	s_waitcnt lgkmcnt(4)
	v_mfma_f32_32x32x16_bf16 v[96:111], v[228:231], v[156:159], v[96:111]
	ds_read_b128 v[228:231], v142 offset:57472
	s_waitcnt lgkmcnt(4)
	v_mfma_f32_32x32x16_bf16 v[80:95], v[232:235], v[156:159], v[80:95]
	ds_read_b128 v[232:235], v143 offset:49280
	s_waitcnt lgkmcnt(4)
	v_mfma_f32_32x32x16_bf16 v[96:111], v[8:11], v[152:155], v[96:111]
	ds_read_b128 v[8:11], v143 offset:57472
	s_waitcnt lgkmcnt(4)
	v_mfma_f32_32x32x16_bf16 v[80:95], v[220:223], v[152:155], v[80:95]
	s_waitcnt lgkmcnt(3)
	v_mfma_f32_32x32x16_bf16 v[96:111], v[224:227], v[148:151], v[96:111]
	s_waitcnt lgkmcnt(2)
	v_mfma_f32_32x32x16_bf16 v[80:95], v[228:231], v[148:151], v[80:95]
	s_waitcnt lgkmcnt(1)
	v_mfma_f32_32x32x16_bf16 v[96:111], v[232:235], v[144:147], v[96:111]
	s_waitcnt lgkmcnt(0)
	v_mfma_f32_32x32x16_bf16 v[80:95], v[8:11], v[144:147], v[80:95]
	s_setprio 0
	v_exp_f32_e32 v203, v7
	v_add_f32_e32 v7, 0, v125
	v_add_f32_e32 v7, v126, v7
	v_add_f32_e32 v7, v127, v7
	v_add_f32_e32 v7, v130, v7
	v_add_f32_e32 v7, v131, v7
	v_add_f32_e32 v7, v12, v7
	v_add_f32_e32 v7, v13, v7
	v_add_f32_e32 v7, v14, v7
	v_add_f32_e32 v7, v15, v7
	v_add_f32_e32 v7, v132, v7
	v_add_f32_e32 v7, v133, v7
	v_add_f32_e32 v7, v134, v7
	v_exp_f32_e32 v9, v112
	v_add_f32_e32 v7, v135, v7
	v_exp_f32_e32 v140, v113
	v_add_f32_e32 v7, v136, v7
	v_exp_f32_e32 v141, v114
	v_add_f32_e32 v7, v137, v7
	v_exp_f32_e32 v142, v115
	v_add_f32_e32 v7, v138, v7
	v_exp_f32_e32 v143, v116
	v_add_f32_e32 v7, v9, v7
	v_exp_f32_e32 v201, v117
	v_add_f32_e32 v7, v140, v7
	v_exp_f32_e32 v202, v118
	v_add_f32_e32 v7, v141, v7
	v_exp_f32_e32 v119, v119
	v_add_f32_e32 v7, v142, v7
	v_exp_f32_e32 v120, v120
	v_add_f32_e32 v7, v143, v7
	v_exp_f32_e32 v121, v121
	v_add_f32_e32 v7, v201, v7
	v_exp_f32_e32 v122, v122
	v_add_f32_e32 v7, v202, v7
	v_exp_f32_e32 v123, v123
	v_add_f32_e32 v7, v119, v7
	v_exp_f32_e32 v124, v124
	v_add_f32_e32 v7, v120, v7
	v_add_f32_e32 v7, v121, v7
	v_exp_f32_e32 v139, v139
	v_add_f32_e32 v7, v122, v7
	v_exp_f32_e32 v5, v5
	v_add_f32_e32 v7, v123, v7
	v_add_f32_e32 v7, v124, v7
	v_add_f32_e32 v7, v203, v7
	v_add_f32_e32 v7, v139, v7
	v_add_f32_e32 v7, v5, v7
	v_mov_b32_e32 v8, v7
	s_nop 1
	v_permlane32_swap_b32_e32 v7, v8
	v_cvt_pk_bf16_f32 v10, v125, v126
	v_cvt_pk_bf16_f32 v11, v127, v130
	v_cvt_pk_bf16_f32 v12, v131, v12
	v_cvt_pk_bf16_f32 v13, v13, v14
	v_cvt_pk_bf16_f32 v112, v15, v132
	v_cvt_pk_bf16_f32 v113, v133, v134
	v_cvt_pk_bf16_f32 v114, v135, v136
	v_cvt_pk_bf16_f32 v115, v137, v138
	v_cvt_pk_bf16_f32 v116, v9, v140
	v_cvt_pk_bf16_f32 v117, v141, v142
	v_cvt_pk_bf16_f32 v118, v143, v201
	v_cvt_pk_bf16_f32 v119, v202, v119
	v_cvt_pk_bf16_f32 v120, v120, v121
	v_cvt_pk_bf16_f32 v121, v122, v123
	v_cvt_pk_bf16_f32 v122, v124, v203
	v_cvt_pk_bf16_f32 v123, v139, v5
	s_nop 0
	v_permlane32_swap_b32_e32 v10, v12
	v_permlane32_swap_b32_e32 v11, v13
	v_permlane32_swap_b32_e32 v112, v114
	v_permlane32_swap_b32_e32 v113, v115
	v_permlane32_swap_b32_e32 v116, v118
	v_permlane32_swap_b32_e32 v117, v119
	v_permlane32_swap_b32_e32 v120, v122
	v_permlane32_swap_b32_e32 v121, v123
	v_add_u32_e32 v5, s66, v193
	ds_read_b64_tr_b16 v[124:125], v5 offset:0
	ds_read_b64_tr_b16 v[126:127], v5 offset:0x800
	ds_read_b64_tr_b16 v[130:131], v5 offset:0x1000
	ds_read_b64_tr_b16 v[132:133], v5 offset:0x1800
	ds_read_b64_tr_b16 v[134:135], v5 offset:0x2000
	ds_read_b64_tr_b16 v[136:137], v5 offset:0x2800
	ds_read_b64_tr_b16 v[138:139], v5 offset:0x3000
	ds_read_b64_tr_b16 v[140:141], v5 offset:0x3800
	s_waitcnt lgkmcnt(6)
	s_nop 0
	v_mfma_f32_32x32x16_bf16 v[16:31], v[10:13], v[124:127], v[16:31]
	ds_read_b64_tr_b16 v[124:125], v5 offset:0x200
	ds_read_b64_tr_b16 v[126:127], v5 offset:0xa00
	s_waitcnt lgkmcnt(6)
	v_mfma_f32_32x32x16_bf16 v[16:31], v[112:115], v[130:133], v[16:31]
	ds_read_b64_tr_b16 v[130:131], v5 offset:0x1200
	ds_read_b64_tr_b16 v[132:133], v5 offset:0x1a00
	s_waitcnt lgkmcnt(6)
	v_mfma_f32_32x32x16_bf16 v[16:31], v[116:119], v[134:137], v[16:31]
	ds_read_b64_tr_b16 v[134:135], v5 offset:0x2200
	ds_read_b64_tr_b16 v[136:137], v5 offset:0x2a00
	s_waitcnt lgkmcnt(6)
	v_mfma_f32_32x32x16_bf16 v[16:31], v[120:123], v[138:141], v[16:31]
	ds_read_b64_tr_b16 v[138:139], v5 offset:0x3200
	ds_read_b64_tr_b16 v[140:141], v5 offset:0x3a00
	s_waitcnt lgkmcnt(6)
	v_mfma_f32_32x32x16_bf16 v[48:63], v[10:13], v[124:127], v[48:63]
	ds_read_b64_tr_b16 v[124:125], v5 offset:0x400
	ds_read_b64_tr_b16 v[126:127], v5 offset:0xc00
	s_waitcnt lgkmcnt(6)
	v_mfma_f32_32x32x16_bf16 v[48:63], v[112:115], v[130:133], v[48:63]
	ds_read_b64_tr_b16 v[130:131], v5 offset:0x1400
	ds_read_b64_tr_b16 v[132:133], v5 offset:0x1c00
	s_waitcnt lgkmcnt(6)
	v_mfma_f32_32x32x16_bf16 v[48:63], v[116:119], v[134:137], v[48:63]
	ds_read_b64_tr_b16 v[134:135], v5 offset:0x2400
	ds_read_b64_tr_b16 v[136:137], v5 offset:0x2c00
	s_waitcnt lgkmcnt(6)
	v_mfma_f32_32x32x16_bf16 v[48:63], v[120:123], v[138:141], v[48:63]
	ds_read_b64_tr_b16 v[138:139], v5 offset:0x3400
	ds_read_b64_tr_b16 v[140:141], v5 offset:0x3c00
	s_waitcnt lgkmcnt(6)
	v_mfma_f32_32x32x16_bf16 v[64:79], v[10:13], v[124:127], v[64:79]
	ds_read_b64_tr_b16 v[124:125], v5 offset:0x600
	ds_read_b64_tr_b16 v[126:127], v5 offset:0xe00
	s_waitcnt lgkmcnt(6)
	v_mfma_f32_32x32x16_bf16 v[64:79], v[112:115], v[130:133], v[64:79]
	ds_read_b64_tr_b16 v[130:131], v5 offset:0x1600
	ds_read_b64_tr_b16 v[132:133], v5 offset:0x1e00
	s_waitcnt lgkmcnt(6)
	v_mfma_f32_32x32x16_bf16 v[64:79], v[116:119], v[134:137], v[64:79]
	ds_read_b64_tr_b16 v[134:135], v5 offset:0x2600
	ds_read_b64_tr_b16 v[136:137], v5 offset:0x2e00
	s_waitcnt lgkmcnt(6)
	v_mfma_f32_32x32x16_bf16 v[64:79], v[120:123], v[138:141], v[64:79]
	ds_read_b64_tr_b16 v[138:139], v5 offset:0x3600
	ds_read_b64_tr_b16 v[140:141], v5 offset:0x3e00
	s_waitcnt lgkmcnt(6)
	v_mfma_f32_32x32x16_bf16 v[32:47], v[10:13], v[124:127], v[32:47]
	s_cmp_le_i32 s70, s69
	s_waitcnt lgkmcnt(4)
	v_mfma_f32_32x32x16_bf16 v[32:47], v[112:115], v[130:133], v[32:47]
	s_waitcnt lgkmcnt(2)
	v_mfma_f32_32x32x16_bf16 v[32:47], v[116:119], v[134:137], v[32:47]
	s_waitcnt lgkmcnt(0)
	v_mfma_f32_32x32x16_bf16 v[32:47], v[120:123], v[138:141], v[32:47]
	s_cbranch_scc1 .LBB0_1202
	v_add_u32_e32 v5, 0x4000007b, v1
	v_cmp_gt_u32_e32 vcc, 2.0, v5
	v_add_u32_e32 v5, 0x5b, v1
	s_nop 0
	v_cndmask_b32_e32 v96, v179, v96, vcc
	v_cmp_lt_u32_e32 vcc, s96, v5
	v_add_u32_e32 v5, 0x7a, v1
	s_nop 0
	v_cndmask_b32_e32 v80, v179, v80, vcc
	v_cmp_lt_u32_e32 vcc, s96, v5
	v_add_u32_e32 v5, 0x5a, v1
	s_nop 0
	v_cndmask_b32_e32 v97, v179, v97, vcc
	v_cmp_lt_u32_e32 vcc, s96, v5
	v_add_u32_e32 v5, 0x79, v1
	s_nop 0
	v_cndmask_b32_e32 v81, v179, v81, vcc
	v_cmp_lt_u32_e32 vcc, s96, v5
	v_add_u32_e32 v5, 0x59, v1
	s_nop 0
	v_cndmask_b32_e32 v98, v179, v98, vcc
	v_cmp_lt_u32_e32 vcc, s96, v5
	v_add_u32_e32 v5, 0x78, v1
	s_nop 0
	v_cndmask_b32_e32 v82, v179, v82, vcc
	v_cmp_lt_u32_e32 vcc, s96, v5
	v_add_u32_e32 v5, 0x58, v1
	s_nop 0
	v_cndmask_b32_e32 v99, v179, v99, vcc
	v_cmp_lt_u32_e32 vcc, s96, v5
	v_add_u32_e32 v5, 0x73, v1
	s_nop 0
	v_cndmask_b32_e32 v83, v179, v83, vcc
	v_cmp_lt_u32_e32 vcc, s96, v5
	v_add_u32_e32 v5, 0x53, v1
	s_nop 0
	v_cndmask_b32_e32 v100, v179, v100, vcc
	v_cmp_lt_u32_e32 vcc, s96, v5
	v_add_u32_e32 v5, 0x72, v1
	s_nop 0
	v_cndmask_b32_e32 v84, v179, v84, vcc
	v_cmp_lt_u32_e32 vcc, s96, v5
	v_add_u32_e32 v5, 0x52, v1
	s_nop 0
	v_cndmask_b32_e32 v101, v179, v101, vcc
	v_cmp_lt_u32_e32 vcc, s96, v5
	v_add_u32_e32 v5, 0x71, v1
	s_nop 0
	v_cndmask_b32_e32 v85, v179, v85, vcc
	v_cmp_lt_u32_e32 vcc, s96, v5
	v_add_u32_e32 v5, 0x51, v1
	s_nop 0
	v_cndmask_b32_e32 v102, v179, v102, vcc
	v_cmp_lt_u32_e32 vcc, s96, v5
	v_add_u32_e32 v5, 0x70, v1
	s_nop 0
	v_cndmask_b32_e32 v86, v179, v86, vcc
	v_cmp_lt_u32_e32 vcc, s96, v5
	v_add_u32_e32 v5, 0x50, v1
	s_nop 0
	v_cndmask_b32_e32 v103, v179, v103, vcc
	v_cmp_lt_u32_e32 vcc, s96, v5
	v_add_u32_e32 v5, 0x6b, v1
	s_nop 0
	v_cndmask_b32_e32 v87, v179, v87, vcc
	v_cmp_lt_u32_e32 vcc, s96, v5
	v_add_u32_e32 v5, 0x4b, v1
	s_nop 0
	v_cndmask_b32_e32 v104, v179, v104, vcc
	v_cmp_lt_u32_e32 vcc, s96, v5
	v_add_u32_e32 v5, 0x6a, v1
	s_nop 0
	v_cndmask_b32_e32 v88, v179, v88, vcc
	v_cmp_lt_u32_e32 vcc, s96, v5
	v_add_u32_e32 v5, 0x4a, v1
	s_nop 0
	v_cndmask_b32_e32 v105, v179, v105, vcc
	v_cmp_lt_u32_e32 vcc, s96, v5
	v_add_u32_e32 v5, 0x69, v1
	s_nop 0
	v_cndmask_b32_e32 v89, v179, v89, vcc
	v_cmp_lt_u32_e32 vcc, s96, v5
	v_add_u32_e32 v5, 0x49, v1
	s_nop 0
	v_cndmask_b32_e32 v106, v179, v106, vcc
	v_cmp_lt_u32_e32 vcc, s96, v5
	v_add_u32_e32 v5, 0x68, v1
	s_nop 0
	v_cndmask_b32_e32 v90, v179, v90, vcc
	v_cmp_lt_u32_e32 vcc, s96, v5
	v_add_u32_e32 v5, 0x48, v1
	s_nop 0
	v_cndmask_b32_e32 v107, v179, v107, vcc
	v_cmp_lt_u32_e32 vcc, s96, v5
	v_add_u32_e32 v5, 0x63, v1
	s_nop 0
	v_cndmask_b32_e32 v91, v179, v91, vcc
	v_cmp_lt_u32_e32 vcc, s96, v5
	v_add_u32_e32 v5, 0x43, v1
	s_nop 0
	v_cndmask_b32_e32 v108, v179, v108, vcc
	v_cmp_lt_u32_e32 vcc, s96, v5
	v_add_u32_e32 v5, 0x62, v1
	s_nop 0
	v_cndmask_b32_e32 v92, v179, v92, vcc
	v_cmp_lt_u32_e32 vcc, s96, v5
	v_add_u32_e32 v5, 0x42, v1
	s_nop 0
	v_cndmask_b32_e32 v109, v179, v109, vcc
	v_cmp_lt_u32_e32 vcc, s96, v5
	v_add_u32_e32 v5, 0x61, v1
	s_nop 0
	v_cndmask_b32_e32 v93, v179, v93, vcc
	v_cmp_lt_u32_e32 vcc, s96, v5
	v_add_u32_e32 v5, 0x41, v1
	s_nop 0
	v_cndmask_b32_e32 v110, v179, v110, vcc
	v_cmp_lt_u32_e32 vcc, s96, v5
	v_add_u32_e32 v5, 0x60, v1
	s_nop 0
	v_cndmask_b32_e32 v94, v179, v94, vcc
	v_cmp_lt_u32_e32 vcc, s96, v5
	v_add_u32_e32 v5, 64, v1
	s_nop 0
	v_cndmask_b32_e32 v111, v179, v111, vcc
	v_cmp_lt_u32_e32 vcc, s96, v5
	s_nop 1
	v_cndmask_b32_e32 v95, v179, v95, vcc

.LBB0_1216:
	v_exp_f32_e32 v13, v126
	v_exp_f32_e32 v14, v127
	v_exp_f32_e32 v15, v124
	v_exp_f32_e32 v218, v125
	v_exp_f32_e32 v219, v122
	v_exp_f32_e32 v220, v123
	v_exp_f32_e32 v221, v120
	v_exp_f32_e32 v222, v121
	v_exp_f32_e32 v4, v118
	v_exp_f32_e32 v223, v119
	v_exp_f32_e32 v252, v116
	v_exp_f32_e32 v253, v117
	v_exp_f32_e32 v254, v114
	v_exp_f32_e32 v10, v115
	v_exp_f32_e32 v11, v112
	v_exp_f32_e32 v12, v113
	v_add_f32_e32 v1, 0, v215
	s_mov_b64 s[0:1], -1
	s_cmp_ge_i32 s67, s12
	v_add_u32_e32 v3, s8, v193
	v_add_f32_e32 v2, v217, v1
	s_cbranch_scc0 .LBB0_1218
	v_add_f32_e32 v1, v213, v2
	v_add_f32_e32 v1, v216, v1
	v_add_f32_e32 v1, v211, v1
	v_add_f32_e32 v1, v214, v1
	v_add_f32_e32 v1, v210, v1
	v_add_f32_e32 v1, v212, v1
	v_add_f32_e32 v1, v205, v1
	v_add_f32_e32 v1, v208, v1
	v_add_f32_e32 v1, v203, v1
	v_add_f32_e32 v1, v206, v1
	v_add_f32_e32 v1, v202, v1
	v_add_f32_e32 v1, v209, v1
	v_add_f32_e32 v1, v204, v1
	v_add_f32_e32 v1, v207, v1
	v_add_f32_e32 v1, v13, v1
	v_add_f32_e32 v1, v14, v1
	v_add_f32_e32 v1, v15, v1
	v_add_f32_e32 v1, v218, v1
	v_add_f32_e32 v1, v219, v1
	v_add_f32_e32 v1, v220, v1
	v_add_f32_e32 v1, v221, v1
	v_add_f32_e32 v1, v222, v1
	v_add_f32_e32 v1, v4, v1
	v_add_f32_e32 v1, v223, v1
	v_add_f32_e32 v1, v252, v1
	v_add_f32_e32 v1, v253, v1
	v_add_f32_e32 v1, v254, v1
	v_add_f32_e32 v1, v10, v1
	v_add_f32_e32 v1, v11, v1
	v_add_f32_e32 v1, v12, v1
	v_mov_b32_e32 v6, v1
	s_nop 1
	v_permlane32_swap_b32_e32 v1, v6
	v_add_f32_e32 v1, v1, v6
	v_fmac_f32_e32 v1, v194, v5
	v_cvt_pk_bf16_f32 v224, v215, v217
	v_cvt_pk_bf16_f32 v225, v213, v216
	v_cvt_pk_bf16_f32 v226, v211, v214
	v_cvt_pk_bf16_f32 v227, v210, v212
	v_cvt_pk_bf16_f32 v228, v205, v208
	v_cvt_pk_bf16_f32 v229, v203, v206
	v_cvt_pk_bf16_f32 v230, v202, v209
	v_cvt_pk_bf16_f32 v231, v204, v207
	v_cvt_pk_bf16_f32 v232, v13, v14
	v_cvt_pk_bf16_f32 v233, v15, v218
	v_cvt_pk_bf16_f32 v234, v219, v220
	v_cvt_pk_bf16_f32 v235, v221, v222
	v_cvt_pk_bf16_f32 v236, v4, v223
	v_cvt_pk_bf16_f32 v237, v252, v253
	v_cvt_pk_bf16_f32 v238, v254, v10
	v_cvt_pk_bf16_f32 v239, v11, v12
	s_nop 0
	v_permlane32_swap_b32_e32 v224, v226
	v_permlane32_swap_b32_e32 v225, v227
	v_permlane32_swap_b32_e32 v228, v230
	v_permlane32_swap_b32_e32 v229, v231
	v_permlane32_swap_b32_e32 v232, v234
	v_permlane32_swap_b32_e32 v233, v235
	v_permlane32_swap_b32_e32 v236, v238
	v_permlane32_swap_b32_e32 v237, v239
	ds_read_b64_tr_b16 v[96:97], v3 offset:0
	ds_read_b64_tr_b16 v[98:99], v3 offset:0x800
	ds_read_b64_tr_b16 v[100:101], v3 offset:0x1000
	ds_read_b64_tr_b16 v[102:103], v3 offset:0x1800
	ds_read_b64_tr_b16 v[104:105], v3 offset:0x2000
	ds_read_b64_tr_b16 v[106:107], v3 offset:0x2800
	ds_read_b64_tr_b16 v[108:109], v3 offset:0x3000
	ds_read_b64_tr_b16 v[110:111], v3 offset:0x3800
	s_waitcnt lgkmcnt(6)
	s_nop 0
	v_mfma_f32_32x32x16_bf16 v[80:95], v[224:227], v[96:99], v[16:31]
	ds_read_b64_tr_b16 v[112:113], v3 offset:0x200
	ds_read_b64_tr_b16 v[114:115], v3 offset:0xa00
	ds_read_b64_tr_b16 v[116:117], v3 offset:0x1200
	ds_read_b64_tr_b16 v[118:119], v3 offset:0x1a00
	ds_read_b64_tr_b16 v[120:121], v3 offset:0x2200
	ds_read_b64_tr_b16 v[122:123], v3 offset:0x2a00
	ds_read_b64_tr_b16 v[124:125], v3 offset:0x3200
	s_waitcnt lgkmcnt(6)
	v_mfma_f32_32x32x16_bf16 v[80:95], v[228:231], v[100:103], v[80:95]
	ds_read_b64_tr_b16 v[126:127], v3 offset:0x3a00
	s_waitcnt lgkmcnt(6)
	v_mfma_f32_32x32x16_bf16 v[80:95], v[232:235], v[104:107], v[80:95]
	s_waitcnt lgkmcnt(6)
	v_mfma_f32_32x32x16_bf16 v[80:95], v[236:239], v[108:111], v[80:95]
	s_waitcnt lgkmcnt(6)
	v_mfma_f32_32x32x16_bf16 v[96:111], v[224:227], v[112:115], v[48:63]
	ds_read_b64_tr_b16 v[128:129], v3 offset:0x400
	ds_read_b64_tr_b16 v[130:131], v3 offset:0xc00
	ds_read_b64_tr_b16 v[132:133], v3 offset:0x1400
	ds_read_b64_tr_b16 v[134:135], v3 offset:0x1c00
	ds_read_b64_tr_b16 v[136:137], v3 offset:0x2400
	ds_read_b64_tr_b16 v[138:139], v3 offset:0x2c00
	ds_read_b64_tr_b16 v[140:141], v3 offset:0x3400
	s_waitcnt lgkmcnt(6)
	v_mfma_f32_32x32x16_bf16 v[96:111], v[228:231], v[116:119], v[96:111]
	ds_read_b64_tr_b16 v[142:143], v3 offset:0x3c00
	s_waitcnt lgkmcnt(6)
	v_mfma_f32_32x32x16_bf16 v[96:111], v[232:235], v[120:123], v[96:111]
	s_waitcnt lgkmcnt(6)
	v_mfma_f32_32x32x16_bf16 v[96:111], v[236:239], v[124:127], v[96:111]
	s_waitcnt lgkmcnt(6)
	v_mfma_f32_32x32x16_bf16 v[112:127], v[224:227], v[128:131], v[64:79]
	ds_read_b64_tr_b16 v[240:241], v3 offset:0x600
	ds_read_b64_tr_b16 v[242:243], v3 offset:0xe00
	ds_read_b64_tr_b16 v[244:245], v3 offset:0x1600
	ds_read_b64_tr_b16 v[246:247], v3 offset:0x1e00
	ds_read_b64_tr_b16 v[248:249], v3 offset:0x2600
	ds_read_b64_tr_b16 v[250:251], v3 offset:0x2e00
	ds_read_b64_tr_b16 v[6:7], v3 offset:0x3600
	s_waitcnt lgkmcnt(6)
	v_mfma_f32_32x32x16_bf16 v[112:127], v[228:231], v[132:135], v[112:127]
	ds_read_b64_tr_b16 v[8:9], v3 offset:0x3e00
	s_waitcnt lgkmcnt(6)
	v_mfma_f32_32x32x16_bf16 v[112:127], v[232:235], v[136:139], v[112:127]
	s_waitcnt lgkmcnt(6)
	v_mfma_f32_32x32x16_bf16 v[112:127], v[236:239], v[140:143], v[112:127]
	s_waitcnt lgkmcnt(6)
	v_mfma_f32_32x32x16_bf16 v[128:143], v[224:227], v[240:243], v[32:47]
	s_mov_b64 s[0:1], 0
	s_waitcnt lgkmcnt(4)
	v_mfma_f32_32x32x16_bf16 v[128:143], v[228:231], v[244:247], v[128:143]
	s_waitcnt lgkmcnt(2)
	v_mfma_f32_32x32x16_bf16 v[128:143], v[232:235], v[248:251], v[128:143]
	s_waitcnt lgkmcnt(0)
	v_mfma_f32_32x32x16_bf16 v[128:143], v[236:239], v[6:9], v[128:143]
.LBB0_1218:
	s_andn2_b64 vcc, exec, s[0:1]
	s_cbranch_vccnz .LBB0_1226
	s_ashr_i32 s0, s53, 8
	s_lshl_b32 s0, s0, 2
	s_add_i32 s0, s0, 0
	v_add_u32_e32 v1, s0, v195
	v_add_u32_e32 v1, 0x18800, v1
	ds_read_b128 v[96:99], v1
	ds_read_b128 v[100:103], v1 offset:32
	ds_read_b128 v[80:83], v1 offset:128
	ds_read_b128 v[84:87], v1 offset:160
	ds_read_b128 v[104:107], v1 offset:64
	ds_read_b128 v[108:111], v1 offset:96
	ds_read_b128 v[88:91], v1 offset:192
	ds_read_b128 v[92:95], v1 offset:224
	s_add_i32 s0, s53, 0
	v_add3_u32 v1, s0, v197, v196
	v_add3_u32 v6, s0, v198, v196
	v_add3_u32 v7, s0, v199, v196
	v_add3_u32 v8, s0, v200, v196
	s_setprio 1
	ds_read_b128 v[112:115], v1 offset:49152
	ds_read_b128 v[116:119], v1 offset:49280
	s_waitcnt lgkmcnt(1)
	v_mfma_f32_32x32x16_bf16 v[96:111], v[112:115], v[172:175], v[96:111]
	ds_read_b128 v[112:115], v1 offset:57344
	ds_read_b128 v[120:123], v1 offset:57472
	s_waitcnt lgkmcnt(1)
	v_mfma_f32_32x32x16_bf16 v[80:95], v[112:115], v[172:175], v[80:95]
	ds_read_b128 v[112:115], v6 offset:49152
	ds_read_b128 v[124:127], v6 offset:49280
	s_waitcnt lgkmcnt(1)
	v_mfma_f32_32x32x16_bf16 v[96:111], v[112:115], v[168:171], v[96:111]
	ds_read_b128 v[112:115], v6 offset:57344
	ds_read_b128 v[128:131], v6 offset:57472
	s_waitcnt lgkmcnt(1)
	v_mfma_f32_32x32x16_bf16 v[80:95], v[112:115], v[168:171], v[80:95]
	ds_read_b128 v[112:115], v7 offset:49152
	ds_read_b128 v[132:135], v7 offset:49280
	s_waitcnt lgkmcnt(1)
	v_mfma_f32_32x32x16_bf16 v[96:111], v[112:115], v[164:167], v[96:111]
	ds_read_b128 v[112:115], v7 offset:57344
	ds_read_b128 v[136:139], v7 offset:57472
	s_waitcnt lgkmcnt(1)
	v_mfma_f32_32x32x16_bf16 v[80:95], v[112:115], v[164:167], v[80:95]
	ds_read_b128 v[112:115], v8 offset:49152
	ds_read_b128 v[140:143], v8 offset:49280
	s_waitcnt lgkmcnt(1)
	v_mfma_f32_32x32x16_bf16 v[96:111], v[112:115], v[160:163], v[96:111]
	ds_read_b128 v[112:115], v8 offset:57344
	ds_read_b128 v[164:167], v8 offset:57472
	s_waitcnt lgkmcnt(1)
	v_mfma_f32_32x32x16_bf16 v[80:95], v[112:115], v[160:163], v[80:95]
	v_mfma_f32_32x32x16_bf16 v[96:111], v[116:119], v[156:159], v[96:111]
	v_mfma_f32_32x32x16_bf16 v[80:95], v[120:123], v[156:159], v[80:95]
	v_mfma_f32_32x32x16_bf16 v[96:111], v[124:127], v[152:155], v[96:111]
	v_mfma_f32_32x32x16_bf16 v[80:95], v[128:131], v[152:155], v[80:95]
	v_mfma_f32_32x32x16_bf16 v[96:111], v[132:135], v[148:151], v[96:111]
	v_mfma_f32_32x32x16_bf16 v[80:95], v[136:139], v[148:151], v[80:95]
	v_mfma_f32_32x32x16_bf16 v[96:111], v[140:143], v[144:147], v[96:111]
	s_waitcnt lgkmcnt(0)
	v_mfma_f32_32x32x16_bf16 v[80:95], v[164:167], v[144:147], v[80:95]
	s_setprio 0
	v_add_f32_e32 v1, v213, v2
	v_add_f32_e32 v1, v216, v1
	v_add_f32_e32 v1, v211, v1
	v_add_f32_e32 v1, v214, v1
	v_add_f32_e32 v1, v210, v1
	v_add_f32_e32 v1, v212, v1
	v_add_f32_e32 v1, v205, v1
	v_add_f32_e32 v1, v208, v1
	v_add_f32_e32 v1, v203, v1
	v_add_f32_e32 v1, v206, v1
	v_add_f32_e32 v1, v202, v1
	v_add_f32_e32 v1, v209, v1
	v_add_f32_e32 v1, v204, v1
	v_add_f32_e32 v1, v207, v1
	v_add_f32_e32 v1, v13, v1
	v_add_f32_e32 v1, v14, v1
	v_add_f32_e32 v1, v15, v1
	v_add_f32_e32 v1, v218, v1
	v_add_f32_e32 v1, v219, v1
	v_add_f32_e32 v1, v220, v1
	v_add_f32_e32 v1, v221, v1
	v_add_f32_e32 v1, v222, v1
	v_add_f32_e32 v1, v4, v1
	v_add_f32_e32 v1, v223, v1
	v_add_f32_e32 v1, v252, v1
	v_add_f32_e32 v1, v253, v1
	v_add_f32_e32 v1, v254, v1
	v_add_f32_e32 v1, v10, v1
	v_add_f32_e32 v1, v11, v1
	v_add_f32_e32 v1, v12, v1
	v_mov_b32_e32 v2, v1
	s_nop 1
	v_permlane32_swap_b32_e32 v1, v2
	v_cvt_pk_bf16_f32 v112, v215, v217
	v_cvt_pk_bf16_f32 v113, v213, v216
	v_cvt_pk_bf16_f32 v114, v211, v214
	v_cvt_pk_bf16_f32 v115, v210, v212
	v_cvt_pk_bf16_f32 v116, v205, v208
	v_cvt_pk_bf16_f32 v117, v203, v206
	v_cvt_pk_bf16_f32 v118, v202, v209
	v_cvt_pk_bf16_f32 v119, v204, v207
	v_cvt_pk_bf16_f32 v120, v13, v14
	v_cvt_pk_bf16_f32 v121, v15, v218
	v_cvt_pk_bf16_f32 v122, v219, v220
	v_cvt_pk_bf16_f32 v123, v221, v222
	v_cvt_pk_bf16_f32 v6, v4, v223
	v_cvt_pk_bf16_f32 v7, v252, v253
	v_cvt_pk_bf16_f32 v8, v254, v10
	v_cvt_pk_bf16_f32 v9, v11, v12
	s_nop 0
	v_permlane32_swap_b32_e32 v112, v114
	v_permlane32_swap_b32_e32 v113, v115
	v_permlane32_swap_b32_e32 v116, v118
	v_permlane32_swap_b32_e32 v117, v119
	v_permlane32_swap_b32_e32 v120, v122
	v_permlane32_swap_b32_e32 v121, v123
	v_permlane32_swap_b32_e32 v6, v8
	v_permlane32_swap_b32_e32 v7, v9
	ds_read_b64_tr_b16 v[10:11], v3 offset:0
	ds_read_b64_tr_b16 v[12:13], v3 offset:0x800
	ds_read_b64_tr_b16 v[124:125], v3 offset:0x1000
	ds_read_b64_tr_b16 v[126:127], v3 offset:0x1800
	ds_read_b64_tr_b16 v[128:129], v3 offset:0x2000
	ds_read_b64_tr_b16 v[130:131], v3 offset:0x2800
	ds_read_b64_tr_b16 v[132:133], v3 offset:0x3000
	ds_read_b64_tr_b16 v[134:135], v3 offset:0x3800
	s_waitcnt lgkmcnt(6)
	s_nop 0
	v_mfma_f32_32x32x16_bf16 v[16:31], v[112:115], v[10:13], v[16:31]
	ds_read_b64_tr_b16 v[10:11], v3 offset:0x200
	ds_read_b64_tr_b16 v[12:13], v3 offset:0xa00
	s_waitcnt lgkmcnt(6)
	v_mfma_f32_32x32x16_bf16 v[16:31], v[116:119], v[124:127], v[16:31]
	ds_read_b64_tr_b16 v[124:125], v3 offset:0x1200
	ds_read_b64_tr_b16 v[126:127], v3 offset:0x1a00
	s_waitcnt lgkmcnt(6)
	v_mfma_f32_32x32x16_bf16 v[16:31], v[120:123], v[128:131], v[16:31]
	ds_read_b64_tr_b16 v[128:129], v3 offset:0x2200
	ds_read_b64_tr_b16 v[130:131], v3 offset:0x2a00
	ds_read_b64_tr_b16 v[136:137], v3 offset:0x3200
	ds_read_b64_tr_b16 v[138:139], v3 offset:0x3a00
	s_waitcnt lgkmcnt(6)
	v_mfma_f32_32x32x16_bf16 v[16:31], v[6:9], v[132:135], v[16:31]
	s_waitcnt lgkmcnt(6)
	v_mfma_f32_32x32x16_bf16 v[48:63], v[112:115], v[10:13], v[48:63]
	ds_read_b64_tr_b16 v[10:11], v3 offset:0x400
	ds_read_b64_tr_b16 v[12:13], v3 offset:0xc00
	s_waitcnt lgkmcnt(6)
	v_mfma_f32_32x32x16_bf16 v[48:63], v[116:119], v[124:127], v[48:63]
	ds_read_b64_tr_b16 v[124:125], v3 offset:0x1400
	ds_read_b64_tr_b16 v[126:127], v3 offset:0x1c00
	s_waitcnt lgkmcnt(6)
	v_mfma_f32_32x32x16_bf16 v[48:63], v[120:123], v[128:131], v[48:63]
	ds_read_b64_tr_b16 v[128:129], v3 offset:0x2400
	ds_read_b64_tr_b16 v[130:131], v3 offset:0x2c00
	ds_read_b64_tr_b16 v[132:133], v3 offset:0x3400
	ds_read_b64_tr_b16 v[134:135], v3 offset:0x3c00
	s_waitcnt lgkmcnt(6)
	v_mfma_f32_32x32x16_bf16 v[48:63], v[6:9], v[136:139], v[48:63]
	s_waitcnt lgkmcnt(6)
	v_mfma_f32_32x32x16_bf16 v[64:79], v[112:115], v[10:13], v[64:79]
	ds_read_b64_tr_b16 v[10:11], v3 offset:0x600
	ds_read_b64_tr_b16 v[12:13], v3 offset:0xe00
	s_waitcnt lgkmcnt(6)
	v_mfma_f32_32x32x16_bf16 v[64:79], v[116:119], v[124:127], v[64:79]
	ds_read_b64_tr_b16 v[124:125], v3 offset:0x1600
	ds_read_b64_tr_b16 v[126:127], v3 offset:0x1e00
	s_waitcnt lgkmcnt(6)
	v_mfma_f32_32x32x16_bf16 v[64:79], v[120:123], v[128:131], v[64:79]
	ds_read_b64_tr_b16 v[128:129], v3 offset:0x2600
	ds_read_b64_tr_b16 v[130:131], v3 offset:0x2e00
	ds_read_b64_tr_b16 v[136:137], v3 offset:0x3600
	ds_read_b64_tr_b16 v[138:139], v3 offset:0x3e00
	s_waitcnt lgkmcnt(6)
	v_mfma_f32_32x32x16_bf16 v[64:79], v[6:9], v[132:135], v[64:79]
	s_waitcnt lgkmcnt(6)
	v_mfma_f32_32x32x16_bf16 v[32:47], v[112:115], v[10:13], v[32:47]
	s_sub_i32 s0, s52, s67
	s_lshl_b32 s0, s0, 6
	s_or_b32 s1, s0, 63
	s_cmp_le_i32 s1, s69
	s_waitcnt lgkmcnt(4)
	v_mfma_f32_32x32x16_bf16 v[32:47], v[116:119], v[124:127], v[32:47]
	s_waitcnt lgkmcnt(2)
	v_mfma_f32_32x32x16_bf16 v[32:47], v[120:123], v[128:131], v[32:47]
	s_waitcnt lgkmcnt(0)
	v_mfma_f32_32x32x16_bf16 v[32:47], v[6:9], v[136:139], v[32:47]
	s_cbranch_scc1 .LBB0_1221
	v_subrev_u32_e32 v3, s0, v192
	v_cmp_gt_u32_e32 vcc, 2.0, v3
	v_add_u32_e32 v4, 0xbfffffe0, v3
	s_nop 0
	v_cndmask_b32_e32 v96, v179, v96, vcc
	v_cmp_lt_u32_e32 vcc, s96, v4
	v_add_u32_e32 v4, 0xbfffffff, v3
	s_nop 0
	v_cndmask_b32_e32 v80, v179, v80, vcc
	v_cmp_lt_u32_e32 vcc, s96, v4
	v_add_u32_e32 v4, 0xbfffffdf, v3
	s_nop 0
	v_cndmask_b32_e32 v97, v179, v97, vcc
	v_cmp_lt_u32_e32 vcc, s96, v4
	v_add_u32_e32 v4, 0xbffffffe, v3
	s_nop 0
	v_cndmask_b32_e32 v81, v179, v81, vcc
	v_cmp_lt_u32_e32 vcc, s96, v4
	v_add_u32_e32 v4, 0xbfffffde, v3
	s_nop 0
	v_cndmask_b32_e32 v98, v179, v98, vcc
	v_cmp_lt_u32_e32 vcc, s96, v4
	v_add_u32_e32 v4, 0xbffffffd, v3
	s_nop 0
	v_cndmask_b32_e32 v82, v179, v82, vcc
	v_cmp_lt_u32_e32 vcc, s96, v4
	v_add_u32_e32 v4, 0xbfffffdd, v3
	s_nop 0
	v_cndmask_b32_e32 v99, v179, v99, vcc
	v_cmp_lt_u32_e32 vcc, s96, v4
	v_add_u32_e32 v4, 0xbffffff8, v3
	s_nop 0
	v_cndmask_b32_e32 v83, v179, v83, vcc
	v_cmp_lt_u32_e32 vcc, s96, v4
	v_add_u32_e32 v4, 0xbfffffd8, v3
	s_nop 0
	v_cndmask_b32_e32 v100, v179, v100, vcc
	v_cmp_lt_u32_e32 vcc, s96, v4
	v_add_u32_e32 v4, 0xbffffff7, v3
	s_nop 0
	v_cndmask_b32_e32 v84, v179, v84, vcc
	v_cmp_lt_u32_e32 vcc, s96, v4
	v_add_u32_e32 v4, 0xbfffffd7, v3
	s_nop 0
	v_cndmask_b32_e32 v101, v179, v101, vcc
	v_cmp_lt_u32_e32 vcc, s96, v4
	v_add_u32_e32 v4, 0xbffffff6, v3
	s_nop 0
	v_cndmask_b32_e32 v85, v179, v85, vcc
	v_cmp_lt_u32_e32 vcc, s96, v4
	v_add_u32_e32 v4, 0xbfffffd6, v3
	s_nop 0
	v_cndmask_b32_e32 v102, v179, v102, vcc
	v_cmp_lt_u32_e32 vcc, s96, v4
	v_add_u32_e32 v4, 0xbffffff5, v3
	s_nop 0
	v_cndmask_b32_e32 v86, v179, v86, vcc
	v_cmp_lt_u32_e32 vcc, s96, v4
	v_add_u32_e32 v4, 0xbfffffd5, v3
	s_nop 0
	v_cndmask_b32_e32 v103, v179, v103, vcc
	v_cmp_lt_u32_e32 vcc, s96, v4
	v_add_u32_e32 v4, 0xbffffff0, v3
	s_nop 0
	v_cndmask_b32_e32 v87, v179, v87, vcc
	v_cmp_lt_u32_e32 vcc, s96, v4
	v_add_u32_e32 v4, 0xbfffffd0, v3
	s_nop 0
	v_cndmask_b32_e32 v104, v179, v104, vcc
	v_cmp_lt_u32_e32 vcc, s96, v4
	v_add_u32_e32 v4, 0xbfffffef, v3
	s_nop 0
	v_cndmask_b32_e32 v88, v179, v88, vcc
	v_cmp_lt_u32_e32 vcc, s96, v4
	v_add_u32_e32 v4, 0xbfffffcf, v3
	s_nop 0
	v_cndmask_b32_e32 v105, v179, v105, vcc
	v_cmp_lt_u32_e32 vcc, s96, v4
	v_add_u32_e32 v4, 0xbfffffee, v3
	s_nop 0
	v_cndmask_b32_e32 v89, v179, v89, vcc
	v_cmp_lt_u32_e32 vcc, s96, v4
	v_add_u32_e32 v4, 0xbfffffce, v3
	s_nop 0
	v_cndmask_b32_e32 v106, v179, v106, vcc
	v_cmp_lt_u32_e32 vcc, s96, v4
	v_add_u32_e32 v4, 0xbfffffed, v3
	s_nop 0
	v_cndmask_b32_e32 v90, v179, v90, vcc
	v_cmp_lt_u32_e32 vcc, s96, v4
	v_add_u32_e32 v4, 0xbfffffcd, v3
	s_nop 0
	v_cndmask_b32_e32 v107, v179, v107, vcc
	v_cmp_lt_u32_e32 vcc, s96, v4
	v_add_u32_e32 v4, 0xbfffffe8, v3
	s_nop 0
	v_cndmask_b32_e32 v91, v179, v91, vcc
	v_cmp_lt_u32_e32 vcc, s96, v4
	v_add_u32_e32 v4, 0xbfffffc8, v3
	s_nop 0
	v_cndmask_b32_e32 v108, v179, v108, vcc
	v_cmp_lt_u32_e32 vcc, s96, v4
	v_add_u32_e32 v4, 0xbfffffe7, v3
	s_nop 0
	v_cndmask_b32_e32 v92, v179, v92, vcc
	v_cmp_lt_u32_e32 vcc, s96, v4
	v_add_u32_e32 v4, 0xbfffffc7, v3
	s_nop 0
	v_cndmask_b32_e32 v109, v179, v109, vcc
	v_cmp_lt_u32_e32 vcc, s96, v4
	v_add_u32_e32 v4, 0xbfffffe6, v3
	s_nop 0
	v_cndmask_b32_e32 v93, v179, v93, vcc
	v_cmp_lt_u32_e32 vcc, s96, v4
	v_add_u32_e32 v4, 0xbfffffc6, v3
	s_nop 0
	v_cndmask_b32_e32 v110, v179, v110, vcc
	v_cmp_lt_u32_e32 vcc, s96, v4
	v_add_u32_e32 v4, 0xbfffffe5, v3
	v_add_u32_e32 v3, 0xbfffffc5, v3
	v_cndmask_b32_e32 v94, v179, v94, vcc
	v_cmp_lt_u32_e32 vcc, s96, v4
	s_nop 1
	v_cndmask_b32_e32 v111, v179, v111, vcc
	v_cmp_lt_u32_e32 vcc, s96, v3
	s_nop 1
	v_cndmask_b32_e32 v95, v179, v95, vcc

.LBB0_1225:
	v_cndmask_b32_e64 v4, v4, v201, s[6:7]
	v_mul_f32_e32 v4, 0xbe0293ee, v4
	v_fmamk_f32 v6, v96, 0x3e0293ee, v4
	v_fmamk_f32 v7, v97, 0x3e0293ee, v4
	v_exp_f32_e32 v6, v6
	v_fmamk_f32 v8, v98, 0x3e0293ee, v4
	v_exp_f32_e32 v7, v7
	v_fmamk_f32 v9, v99, 0x3e0293ee, v4
	v_exp_f32_e32 v8, v8
	v_fmamk_f32 v10, v100, 0x3e0293ee, v4
	v_exp_f32_e32 v9, v9
	v_fmamk_f32 v11, v101, 0x3e0293ee, v4
	v_exp_f32_e32 v10, v10
	v_add_f32_e32 v2, v1, v2
	v_add_f32_e32 v1, 0, v6
	v_fmamk_f32 v12, v102, 0x3e0293ee, v4
	v_exp_f32_e32 v11, v11
	v_add_f32_e32 v1, v7, v1
	v_fmamk_f32 v13, v103, 0x3e0293ee, v4
	v_exp_f32_e32 v12, v12
	v_add_f32_e32 v1, v8, v1
	v_fmamk_f32 v14, v104, 0x3e0293ee, v4
	v_exp_f32_e32 v13, v13
	v_add_f32_e32 v1, v9, v1
	v_fmamk_f32 v15, v105, 0x3e0293ee, v4
	v_exp_f32_e32 v14, v14
	v_add_f32_e32 v1, v10, v1
	v_fmamk_f32 v96, v106, 0x3e0293ee, v4
	v_exp_f32_e32 v15, v15
	v_add_f32_e32 v1, v11, v1
	v_fmamk_f32 v97, v107, 0x3e0293ee, v4
	v_fmamk_f32 v98, v108, 0x3e0293ee, v4
	v_fmamk_f32 v99, v109, 0x3e0293ee, v4
	v_fmamk_f32 v100, v110, 0x3e0293ee, v4
	v_fmamk_f32 v101, v111, 0x3e0293ee, v4
	v_fmamk_f32 v80, v80, 0x3e0293ee, v4
	v_fmamk_f32 v81, v81, 0x3e0293ee, v4
	v_fmamk_f32 v82, v82, 0x3e0293ee, v4
	v_fmamk_f32 v83, v83, 0x3e0293ee, v4
	v_fmamk_f32 v84, v84, 0x3e0293ee, v4
	v_fmamk_f32 v85, v85, 0x3e0293ee, v4
	v_fmamk_f32 v86, v86, 0x3e0293ee, v4
	v_fmamk_f32 v87, v87, 0x3e0293ee, v4
	v_fmamk_f32 v88, v88, 0x3e0293ee, v4
	v_fmamk_f32 v89, v89, 0x3e0293ee, v4
	v_fmamk_f32 v90, v90, 0x3e0293ee, v4
	v_fmamk_f32 v91, v91, 0x3e0293ee, v4
	v_fmamk_f32 v92, v92, 0x3e0293ee, v4
	v_fmamk_f32 v93, v93, 0x3e0293ee, v4
	v_fmamk_f32 v94, v94, 0x3e0293ee, v4
	v_fmac_f32_e32 v4, 0x3e0293ee, v95
	v_exp_f32_e32 v95, v96
	v_add_f32_e32 v1, v12, v1
	v_exp_f32_e32 v96, v97
	v_add_f32_e32 v1, v13, v1
	v_exp_f32_e32 v97, v98
	v_add_f32_e32 v1, v14, v1
	v_exp_f32_e32 v98, v99
	v_add_f32_e32 v1, v15, v1
	v_exp_f32_e32 v99, v100
	v_add_f32_e32 v1, v95, v1
	v_exp_f32_e32 v100, v101
	v_add_f32_e32 v1, v96, v1
	v_exp_f32_e32 v80, v80
	v_add_f32_e32 v1, v97, v1
	v_exp_f32_e32 v81, v81
	v_add_f32_e32 v1, v98, v1
	v_exp_f32_e32 v82, v82
	v_add_f32_e32 v1, v99, v1
	v_exp_f32_e32 v83, v83
	v_add_f32_e32 v1, v100, v1
	v_exp_f32_e32 v84, v84
	v_add_f32_e32 v1, v80, v1
	v_exp_f32_e32 v85, v85
	v_add_f32_e32 v1, v81, v1
	v_exp_f32_e32 v86, v86
	v_add_f32_e32 v1, v82, v1
	v_exp_f32_e32 v87, v87
	v_add_f32_e32 v1, v83, v1
	v_exp_f32_e32 v88, v88
	v_add_f32_e32 v1, v84, v1
	v_exp_f32_e32 v89, v89
	v_add_f32_e32 v1, v85, v1
	v_exp_f32_e32 v90, v90
	v_add_f32_e32 v1, v86, v1
	v_exp_f32_e32 v91, v91
	v_add_f32_e32 v1, v87, v1
	v_exp_f32_e32 v92, v92
	v_add_f32_e32 v1, v88, v1
	v_exp_f32_e32 v93, v93
	v_add_f32_e32 v1, v89, v1
	v_exp_f32_e32 v94, v94
	v_add_f32_e32 v1, v90, v1
	v_exp_f32_e32 v101, v4
	v_add_f32_e32 v1, v91, v1
	v_add_f32_e32 v1, v92, v1
	v_add_f32_e32 v1, v93, v1
	v_add_f32_e32 v1, v94, v1
	v_add_f32_e32 v1, v101, v1
	v_mov_b32_e32 v4, v1
	s_nop 1
	v_permlane32_swap_b32_e32 v1, v4
	v_fmac_f32_e32 v2, v194, v5
	s_waitcnt vmcnt(0) lgkmcnt(0)
	s_barrier
	v_add_f32_e32 v1, v1, v4
	v_fmac_f32_e32 v1, v2, v3
	v_cvt_pk_bf16_f32 v2, v6, v7
	v_cvt_pk_bf16_f32 v3, v8, v9
	v_cvt_pk_bf16_f32 v4, v10, v11
	v_cvt_pk_bf16_f32 v5, v12, v13
	v_cvt_pk_bf16_f32 v6, v14, v15
	v_cvt_pk_bf16_f32 v7, v95, v96
	v_cvt_pk_bf16_f32 v8, v97, v98
	v_cvt_pk_bf16_f32 v9, v99, v100
	v_cvt_pk_bf16_f32 v10, v80, v81
	v_cvt_pk_bf16_f32 v11, v82, v83
	v_cvt_pk_bf16_f32 v12, v84, v85
	v_cvt_pk_bf16_f32 v13, v86, v87
	v_cvt_pk_bf16_f32 v80, v88, v89
	v_cvt_pk_bf16_f32 v81, v90, v91
	v_cvt_pk_bf16_f32 v82, v92, v93
	v_cvt_pk_bf16_f32 v83, v94, v101
	s_nop 0
	v_permlane32_swap_b32_e32 v2, v4
	v_permlane32_swap_b32_e32 v80, v82
	v_permlane32_swap_b32_e32 v81, v83
	v_permlane32_swap_b32_e32 v3, v5
	v_permlane32_swap_b32_e32 v6, v8
	v_permlane32_swap_b32_e32 v7, v9
	v_permlane32_swap_b32_e32 v10, v12
	v_permlane32_swap_b32_e32 v11, v13
	v_add_u32_e32 v14, s53, v193
	ds_read_b64_tr_b16 v[84:85], v14 offset:0
	ds_read_b64_tr_b16 v[86:87], v14 offset:0x800
	ds_read_b64_tr_b16 v[88:89], v14 offset:0x1000
	ds_read_b64_tr_b16 v[90:91], v14 offset:0x1800
	ds_read_b64_tr_b16 v[92:93], v14 offset:0x2000
	ds_read_b64_tr_b16 v[94:95], v14 offset:0x2800
	ds_read_b64_tr_b16 v[96:97], v14 offset:0x3000
	ds_read_b64_tr_b16 v[98:99], v14 offset:0x3800
	s_waitcnt lgkmcnt(6)
	s_nop 0
	v_mfma_f32_32x32x16_bf16 v[16:31], v[2:5], v[84:87], v[16:31]
	ds_read_b64_tr_b16 v[84:85], v14 offset:0x200
	ds_read_b64_tr_b16 v[86:87], v14 offset:0xa00
	s_waitcnt lgkmcnt(6)
	v_mfma_f32_32x32x16_bf16 v[16:31], v[6:9], v[88:91], v[16:31]
	ds_read_b64_tr_b16 v[88:89], v14 offset:0x1200
	ds_read_b64_tr_b16 v[90:91], v14 offset:0x1a00
	s_waitcnt lgkmcnt(6)
	v_mfma_f32_32x32x16_bf16 v[16:31], v[10:13], v[92:95], v[16:31]
	ds_read_b64_tr_b16 v[92:93], v14 offset:0x2200
	ds_read_b64_tr_b16 v[94:95], v14 offset:0x2a00
	ds_read_b64_tr_b16 v[100:101], v14 offset:0x3200
	ds_read_b64_tr_b16 v[102:103], v14 offset:0x3a00
	s_waitcnt lgkmcnt(6)
	v_mfma_f32_32x32x16_bf16 v[16:31], v[80:83], v[96:99], v[16:31]
	s_waitcnt lgkmcnt(6)
	v_mfma_f32_32x32x16_bf16 v[48:63], v[2:5], v[84:87], v[48:63]
	ds_read_b64_tr_b16 v[84:85], v14 offset:0x400
	ds_read_b64_tr_b16 v[86:87], v14 offset:0xc00
	s_waitcnt lgkmcnt(6)
	v_mfma_f32_32x32x16_bf16 v[48:63], v[6:9], v[88:91], v[48:63]
	ds_read_b64_tr_b16 v[88:89], v14 offset:0x1400
	ds_read_b64_tr_b16 v[90:91], v14 offset:0x1c00
	s_waitcnt lgkmcnt(6)
	v_mfma_f32_32x32x16_bf16 v[48:63], v[10:13], v[92:95], v[48:63]
	ds_read_b64_tr_b16 v[92:93], v14 offset:0x2400
	ds_read_b64_tr_b16 v[94:95], v14 offset:0x2c00
	ds_read_b64_tr_b16 v[96:97], v14 offset:0x3400
	ds_read_b64_tr_b16 v[98:99], v14 offset:0x3c00
	s_waitcnt lgkmcnt(6)
	v_mfma_f32_32x32x16_bf16 v[48:63], v[80:83], v[100:103], v[48:63]
	s_waitcnt lgkmcnt(6)
	v_mfma_f32_32x32x16_bf16 v[64:79], v[2:5], v[84:87], v[64:79]
	ds_read_b64_tr_b16 v[84:85], v14 offset:0x600
	ds_read_b64_tr_b16 v[86:87], v14 offset:0xe00
	s_waitcnt lgkmcnt(6)
	v_mfma_f32_32x32x16_bf16 v[64:79], v[6:9], v[88:91], v[64:79]
	ds_read_b64_tr_b16 v[88:89], v14 offset:0x1600
	ds_read_b64_tr_b16 v[90:91], v14 offset:0x1e00
	s_waitcnt lgkmcnt(6)
	v_mfma_f32_32x32x16_bf16 v[64:79], v[10:13], v[92:95], v[64:79]
	ds_read_b64_tr_b16 v[92:93], v14 offset:0x2600
	ds_read_b64_tr_b16 v[94:95], v14 offset:0x2e00
	ds_read_b64_tr_b16 v[100:101], v14 offset:0x3600
	ds_read_b64_tr_b16 v[102:103], v14 offset:0x3e00
	s_waitcnt lgkmcnt(6)
	v_mfma_f32_32x32x16_bf16 v[64:79], v[80:83], v[96:99], v[64:79]
	s_waitcnt lgkmcnt(6)
	v_mfma_f32_32x32x16_bf16 v[32:47], v[2:5], v[84:87], v[32:47]
	s_nop 10
	v_mov_b64_e32 v[126:127], v[78:79]
	s_mov_b32 s68, s53
	s_mov_b32 s65, s66
	s_mov_b32 s53, s8
	v_mov_b64_e32 v[124:125], v[76:77]
	v_mov_b64_e32 v[122:123], v[74:75]
	v_mov_b64_e32 v[120:121], v[72:73]
	s_waitcnt lgkmcnt(4)
	v_mfma_f32_32x32x16_bf16 v[32:47], v[6:9], v[88:91], v[32:47]
	v_mov_b64_e32 v[118:119], v[70:71]
	v_mov_b64_e32 v[116:117], v[68:69]
	v_mov_b64_e32 v[114:115], v[66:67]
	v_mov_b64_e32 v[112:113], v[64:65]
	s_waitcnt lgkmcnt(2)
	v_mfma_f32_32x32x16_bf16 v[32:47], v[10:13], v[92:95], v[32:47]
	s_waitcnt lgkmcnt(0)
	v_mfma_f32_32x32x16_bf16 v[32:47], v[80:83], v[100:103], v[32:47]
	v_mov_b64_e32 v[110:111], v[62:63]
	v_mov_b64_e32 v[94:95], v[30:31]
	v_mov_b64_e32 v[108:109], v[60:61]
	v_mov_b64_e32 v[106:107], v[58:59]
	v_mov_b64_e32 v[104:105], v[56:57]
	v_mov_b64_e32 v[102:103], v[54:55]
	v_mov_b64_e32 v[100:101], v[52:53]
	s_nop 4
	v_mov_b64_e32 v[142:143], v[46:47]
	v_mov_b64_e32 v[98:99], v[50:51]
	v_mov_b64_e32 v[96:97], v[48:49]
	v_mov_b64_e32 v[140:141], v[44:45]
	v_mov_b64_e32 v[138:139], v[42:43]
	v_mov_b64_e32 v[136:137], v[40:41]
	v_mov_b64_e32 v[134:135], v[38:39]
	v_mov_b64_e32 v[132:133], v[36:37]
	v_mov_b64_e32 v[130:131], v[34:35]
	v_mov_b64_e32 v[128:129], v[32:33]
	v_mov_b64_e32 v[92:93], v[28:29]
	v_mov_b64_e32 v[90:91], v[26:27]
	v_mov_b64_e32 v[88:89], v[24:25]
	v_mov_b64_e32 v[86:87], v[22:23]
	v_mov_b64_e32 v[84:85], v[20:21]
	v_mov_b64_e32 v[82:83], v[18:19]
	v_mov_b64_e32 v[80:81], v[16:17]
	s_branch .LBB0_1227
